# scan operand registers re-assigned so the two non-state sources of each packed op sit in different VGPR banks (on top of 100 stolen w_in units)
# baseline (speedup 1.0000x reference)
.LBB0_633:
	s_cmpk_lg_i32 s44, 0x2100
	s_cselect_b64 s[8:9], -1, 0
	v_cndmask_b32_e64 v0, 0, 1, s[8:9]
	v_cmp_ne_u32_e64 s[8:9], 1, v0
	s_and_saveexec_b64 s[34:35], s[2:3]
	s_xor_b64 s[50:51], exec, s[34:35]
	s_cbranch_execz .LBB0_636
	s_and_b64 vcc, exec, s[8:9]
	s_cbranch_vccnz .LBB0_636
	ds_read_b128 v[108:111], v53 offset:768
	ds_read_b32 v242, v65 offset:1280
	ds_read_b128 v[14:17], v53 offset:256
	ds_read_b128 v[10:13], v53
	ds_read_b128 v[18:21], v53 offset:512
	ds_read_b128 v[22:25], v53 offset:1024
	ds_read_b128 v[220:223], v53 offset:2112
	ds_read_b32 v246, v65 offset:2624
	ds_read_b128 v[122:125], v53 offset:1600
	ds_read_b128 v[118:121], v53 offset:1344
	ds_read_b128 v[134:137], v53 offset:1856
	ds_read_b128 v[230:233], v53 offset:2368
	ds_read_b128 v[224:227], v53 offset:3456
	ds_read_b32 v214, v65 offset:3968
	ds_read_b128 v[142:145], v53 offset:2944
	ds_read_b128 v[138:141], v53 offset:2688
	ds_read_b128 v[146:149], v53 offset:3200
	ds_read_b128 v[150:153], v53 offset:3712
	s_waitcnt lgkmcnt(12)
	v_pk_mul_f32 v[108:109], v[108:109], v[242:243] op_sel_hi:[1,0]
	v_pk_mul_f32 v[110:111], v[110:111], v[242:243] op_sel_hi:[1,0]
	v_pk_mul_f32 v[250:251], v[84:85], v[14:15]
	v_pk_fma_f32 v[108:109], v[84:85], v[10:11], v[108:109]
	v_pk_fma_f32 v[250:251], v[86:87], v[16:17], v[250:251]
	s_nop 0
	v_add_f32_e32 v0, v250, v251
	v_pk_fma_f32 v[110:111], v[86:87], v[12:13], v[110:111]
	s_nop 0
	v_add_f32_dpp v0, v0, v0 row_ror:8 row_mask:0xf bank_mask:0xf bound_ctrl:1
	s_waitcnt lgkmcnt(0)
	v_pk_mul_f32 v[220:221], v[220:221], v[246:247] op_sel_hi:[1,0]
	v_add_f32_dpp v0, v0, v0 row_ror:4 row_mask:0xf bank_mask:0xf bound_ctrl:1
	v_pk_mul_f32 v[222:223], v[222:223], v[246:247] op_sel_hi:[1,0]
	ds_read_b128 v[236:239], v53 offset:4800
	ds_read_b32 v234, v65 offset:5312
	ds_read_b128 v[198:201], v53 offset:4288
	v_add_f32_dpp v0, v0, v0 row_ror:2 row_mask:0xf bank_mask:0xf bound_ctrl:1
	ds_read_b128 v[194:197], v53 offset:4032
	ds_read_b128 v[202:205], v53 offset:4544
	ds_read_b128 v[206:209], v53 offset:5056
	v_add_f32_dpp v0, v0, v0 row_ror:1 row_mask:0xf bank_mask:0xf bound_ctrl:1
	v_pk_fma_f32 v[84:85], v[0:1], v[18:19], v[108:109] op_sel_hi:[0,1,1]
	v_pk_fma_f32 v[86:87], v[0:1], v[20:21], v[110:111] op_sel_hi:[0,1,1]
	v_pk_mul_f32 v[250:251], v[84:85], v[122:123]
	v_pk_fma_f32 v[220:221], v[84:85], v[118:119], v[220:221]
	v_pk_fma_f32 v[250:251], v[86:87], v[124:125], v[250:251]
	v_pk_mul_f32 v[186:187], v[84:85], v[22:23]
	v_add_f32_e32 v0, v250, v251
	v_pk_fma_f32 v[222:223], v[86:87], v[120:121], v[222:223]
	v_pk_fma_f32 v[186:187], v[86:87], v[24:25], v[186:187]
	v_add_f32_dpp v0, v0, v0 row_ror:8 row_mask:0xf bank_mask:0xf bound_ctrl:1
	s_waitcnt lgkmcnt(6)
	v_pk_mul_f32 v[224:225], v[224:225], v[214:215] op_sel_hi:[1,0]
	v_add_f32_e32 v218, v186, v187
	v_add_f32_dpp v0, v0, v0 row_ror:4 row_mask:0xf bank_mask:0xf bound_ctrl:1
	v_pk_mul_f32 v[226:227], v[226:227], v[214:215] op_sel_hi:[1,0]
	ds_read_b128 v[108:111], v53 offset:6144
	ds_read_b32 v242, v65 offset:6656
	ds_read_b128 v[14:17], v53 offset:5632
	v_add_f32_dpp v0, v0, v0 row_ror:2 row_mask:0xf bank_mask:0xf bound_ctrl:1
	ds_read_b128 v[10:13], v53 offset:5376
	ds_read_b128 v[18:21], v53 offset:5888
	ds_read_b128 v[22:25], v53 offset:6400
	v_add_f32_dpp v0, v0, v0 row_ror:1 row_mask:0xf bank_mask:0xf bound_ctrl:1
	v_pk_fma_f32 v[84:85], v[0:1], v[134:135], v[220:221] op_sel_hi:[0,1,1]
	v_pk_fma_f32 v[86:87], v[0:1], v[136:137], v[222:223] op_sel_hi:[0,1,1]
	v_pk_mul_f32 v[250:251], v[84:85], v[142:143]
	v_pk_fma_f32 v[224:225], v[84:85], v[138:139], v[224:225]
	v_pk_fma_f32 v[250:251], v[86:87], v[144:145], v[250:251]
	v_pk_mul_f32 v[186:187], v[84:85], v[230:231]
	v_add_f32_e32 v0, v250, v251
	v_pk_fma_f32 v[226:227], v[86:87], v[140:141], v[226:227]
	v_pk_fma_f32 v[186:187], v[86:87], v[232:233], v[186:187]
	v_add_f32_dpp v0, v0, v0 row_ror:8 row_mask:0xf bank_mask:0xf bound_ctrl:1
	s_waitcnt lgkmcnt(6)
	v_pk_mul_f32 v[236:237], v[236:237], v[234:235] op_sel_hi:[1,0]
	v_add_f32_e32 v219, v186, v187
	v_add_f32_dpp v0, v0, v0 row_ror:4 row_mask:0xf bank_mask:0xf bound_ctrl:1
	v_pk_mul_f32 v[238:239], v[238:239], v[234:235] op_sel_hi:[1,0]
	ds_write2st64_b32 v77, v218, v219 offset0:0 offset1:4
	ds_read_b128 v[220:223], v53 offset:7488
	ds_read_b32 v246, v65 offset:8000
	ds_read_b128 v[122:125], v53 offset:6976
	v_add_f32_dpp v0, v0, v0 row_ror:2 row_mask:0xf bank_mask:0xf bound_ctrl:1
	ds_read_b128 v[118:121], v53 offset:6720
	ds_read_b128 v[134:137], v53 offset:7232
	ds_read_b128 v[230:233], v53 offset:7744
	v_add_f32_dpp v0, v0, v0 row_ror:1 row_mask:0xf bank_mask:0xf bound_ctrl:1
	v_pk_fma_f32 v[84:85], v[0:1], v[146:147], v[224:225] op_sel_hi:[0,1,1]
	v_pk_fma_f32 v[86:87], v[0:1], v[148:149], v[226:227] op_sel_hi:[0,1,1]
	v_pk_mul_f32 v[250:251], v[84:85], v[198:199]
	v_pk_fma_f32 v[236:237], v[84:85], v[194:195], v[236:237]
	v_pk_fma_f32 v[250:251], v[86:87], v[200:201], v[250:251]
	v_pk_mul_f32 v[186:187], v[84:85], v[150:151]
	v_add_f32_e32 v0, v250, v251
	v_pk_fma_f32 v[238:239], v[86:87], v[196:197], v[238:239]
	v_pk_fma_f32 v[186:187], v[86:87], v[152:153], v[186:187]
	v_add_f32_dpp v0, v0, v0 row_ror:8 row_mask:0xf bank_mask:0xf bound_ctrl:1
	s_waitcnt lgkmcnt(7)
	v_pk_mul_f32 v[108:109], v[108:109], v[242:243] op_sel_hi:[1,0]
	v_add_f32_e32 v218, v186, v187
	v_add_f32_dpp v0, v0, v0 row_ror:4 row_mask:0xf bank_mask:0xf bound_ctrl:1
	v_pk_mul_f32 v[110:111], v[110:111], v[242:243] op_sel_hi:[1,0]
	ds_read_b128 v[224:227], v53 offset:8832
	ds_read_b32 v214, v65 offset:9344
	ds_read_b128 v[142:145], v53 offset:8320
	v_add_f32_dpp v0, v0, v0 row_ror:2 row_mask:0xf bank_mask:0xf bound_ctrl:1
	ds_read_b128 v[138:141], v53 offset:8064
	ds_read_b128 v[146:149], v53 offset:8576
	ds_read_b128 v[150:153], v53 offset:9088
	v_add_f32_dpp v0, v0, v0 row_ror:1 row_mask:0xf bank_mask:0xf bound_ctrl:1
	v_pk_fma_f32 v[84:85], v[0:1], v[202:203], v[236:237] op_sel_hi:[0,1,1]
	v_pk_fma_f32 v[86:87], v[0:1], v[204:205], v[238:239] op_sel_hi:[0,1,1]
	v_pk_mul_f32 v[250:251], v[84:85], v[14:15]
	v_pk_fma_f32 v[108:109], v[84:85], v[10:11], v[108:109]
	v_pk_fma_f32 v[250:251], v[86:87], v[16:17], v[250:251]
	v_pk_mul_f32 v[186:187], v[84:85], v[206:207]
	v_add_f32_e32 v0, v250, v251
	v_pk_fma_f32 v[110:111], v[86:87], v[12:13], v[110:111]
	v_pk_fma_f32 v[186:187], v[86:87], v[208:209], v[186:187]
	v_add_f32_dpp v0, v0, v0 row_ror:8 row_mask:0xf bank_mask:0xf bound_ctrl:1
	s_waitcnt lgkmcnt(6)
	v_pk_mul_f32 v[220:221], v[220:221], v[246:247] op_sel_hi:[1,0]
	v_add_f32_e32 v219, v186, v187
	v_add_f32_dpp v0, v0, v0 row_ror:4 row_mask:0xf bank_mask:0xf bound_ctrl:1
	v_pk_mul_f32 v[222:223], v[222:223], v[246:247] op_sel_hi:[1,0]
	ds_write2st64_b32 v77, v218, v219 offset0:8 offset1:12
	ds_read_b128 v[236:239], v53 offset:10176
	ds_read_b32 v234, v65 offset:10688
	ds_read_b128 v[198:201], v53 offset:9664
	v_add_f32_dpp v0, v0, v0 row_ror:2 row_mask:0xf bank_mask:0xf bound_ctrl:1
	ds_read_b128 v[194:197], v53 offset:9408
	ds_read_b128 v[202:205], v53 offset:9920
	ds_read_b128 v[206:209], v53 offset:10432
	v_add_f32_dpp v0, v0, v0 row_ror:1 row_mask:0xf bank_mask:0xf bound_ctrl:1
	v_pk_fma_f32 v[84:85], v[0:1], v[18:19], v[108:109] op_sel_hi:[0,1,1]
	v_pk_fma_f32 v[86:87], v[0:1], v[20:21], v[110:111] op_sel_hi:[0,1,1]
	v_pk_mul_f32 v[250:251], v[84:85], v[122:123]
	v_pk_fma_f32 v[220:221], v[84:85], v[118:119], v[220:221]
	v_pk_fma_f32 v[250:251], v[86:87], v[124:125], v[250:251]
	v_pk_mul_f32 v[186:187], v[84:85], v[22:23]
	v_add_f32_e32 v0, v250, v251
	v_pk_fma_f32 v[222:223], v[86:87], v[120:121], v[222:223]
	v_pk_fma_f32 v[186:187], v[86:87], v[24:25], v[186:187]
	v_add_f32_dpp v0, v0, v0 row_ror:8 row_mask:0xf bank_mask:0xf bound_ctrl:1
	s_waitcnt lgkmcnt(7)
	v_pk_mul_f32 v[224:225], v[224:225], v[214:215] op_sel_hi:[1,0]
	v_add_f32_e32 v218, v186, v187
	v_add_f32_dpp v0, v0, v0 row_ror:4 row_mask:0xf bank_mask:0xf bound_ctrl:1
	v_pk_mul_f32 v[226:227], v[226:227], v[214:215] op_sel_hi:[1,0]
	ds_read_b128 v[108:111], v53 offset:11520
	ds_read_b32 v242, v65 offset:12032
	ds_read_b128 v[14:17], v53 offset:11008
	v_add_f32_dpp v0, v0, v0 row_ror:2 row_mask:0xf bank_mask:0xf bound_ctrl:1
	ds_read_b128 v[10:13], v53 offset:10752
	ds_read_b128 v[18:21], v53 offset:11264
	ds_read_b128 v[22:25], v53 offset:11776
	v_add_f32_dpp v0, v0, v0 row_ror:1 row_mask:0xf bank_mask:0xf bound_ctrl:1
	v_pk_fma_f32 v[84:85], v[0:1], v[134:135], v[220:221] op_sel_hi:[0,1,1]
	v_pk_fma_f32 v[86:87], v[0:1], v[136:137], v[222:223] op_sel_hi:[0,1,1]
	v_pk_mul_f32 v[250:251], v[84:85], v[142:143]
	v_pk_fma_f32 v[224:225], v[84:85], v[138:139], v[224:225]
	v_pk_fma_f32 v[250:251], v[86:87], v[144:145], v[250:251]
	v_pk_mul_f32 v[186:187], v[84:85], v[230:231]
	v_add_f32_e32 v0, v250, v251
	v_pk_fma_f32 v[226:227], v[86:87], v[140:141], v[226:227]
	v_pk_fma_f32 v[186:187], v[86:87], v[232:233], v[186:187]
	v_add_f32_dpp v0, v0, v0 row_ror:8 row_mask:0xf bank_mask:0xf bound_ctrl:1
	s_waitcnt lgkmcnt(6)
	v_pk_mul_f32 v[236:237], v[236:237], v[234:235] op_sel_hi:[1,0]
	v_add_f32_e32 v219, v186, v187
	v_add_f32_dpp v0, v0, v0 row_ror:4 row_mask:0xf bank_mask:0xf bound_ctrl:1
	v_pk_mul_f32 v[238:239], v[238:239], v[234:235] op_sel_hi:[1,0]
	ds_write2st64_b32 v77, v218, v219 offset0:16 offset1:20
	ds_read_b128 v[220:223], v53 offset:12864
	ds_read_b32 v246, v65 offset:13376
	ds_read_b128 v[122:125], v53 offset:12352
	v_add_f32_dpp v0, v0, v0 row_ror:2 row_mask:0xf bank_mask:0xf bound_ctrl:1
	ds_read_b128 v[118:121], v53 offset:12096
	ds_read_b128 v[134:137], v53 offset:12608
	ds_read_b128 v[230:233], v53 offset:13120
	v_add_f32_dpp v0, v0, v0 row_ror:1 row_mask:0xf bank_mask:0xf bound_ctrl:1
	v_pk_fma_f32 v[84:85], v[0:1], v[146:147], v[224:225] op_sel_hi:[0,1,1]
	v_pk_fma_f32 v[86:87], v[0:1], v[148:149], v[226:227] op_sel_hi:[0,1,1]
	v_pk_mul_f32 v[250:251], v[84:85], v[198:199]
	v_pk_fma_f32 v[236:237], v[84:85], v[194:195], v[236:237]
	v_pk_fma_f32 v[250:251], v[86:87], v[200:201], v[250:251]
	v_pk_mul_f32 v[186:187], v[84:85], v[150:151]
	v_add_f32_e32 v0, v250, v251
	v_pk_fma_f32 v[238:239], v[86:87], v[196:197], v[238:239]
	v_pk_fma_f32 v[186:187], v[86:87], v[152:153], v[186:187]
	v_add_f32_dpp v0, v0, v0 row_ror:8 row_mask:0xf bank_mask:0xf bound_ctrl:1
	s_waitcnt lgkmcnt(7)
	v_pk_mul_f32 v[108:109], v[108:109], v[242:243] op_sel_hi:[1,0]
	v_add_f32_e32 v218, v186, v187
	v_add_f32_dpp v0, v0, v0 row_ror:4 row_mask:0xf bank_mask:0xf bound_ctrl:1
	v_pk_mul_f32 v[110:111], v[110:111], v[242:243] op_sel_hi:[1,0]
	ds_read_b128 v[224:227], v53 offset:14208
	ds_read_b32 v214, v65 offset:14720
	ds_read_b128 v[142:145], v53 offset:13696
	v_add_f32_dpp v0, v0, v0 row_ror:2 row_mask:0xf bank_mask:0xf bound_ctrl:1
	ds_read_b128 v[138:141], v53 offset:13440
	ds_read_b128 v[146:149], v53 offset:13952
	ds_read_b128 v[150:153], v53 offset:14464
	v_add_f32_dpp v0, v0, v0 row_ror:1 row_mask:0xf bank_mask:0xf bound_ctrl:1
	v_pk_fma_f32 v[84:85], v[0:1], v[202:203], v[236:237] op_sel_hi:[0,1,1]
	v_pk_fma_f32 v[86:87], v[0:1], v[204:205], v[238:239] op_sel_hi:[0,1,1]
	v_pk_mul_f32 v[250:251], v[84:85], v[14:15]
	v_pk_fma_f32 v[108:109], v[84:85], v[10:11], v[108:109]
	v_pk_fma_f32 v[250:251], v[86:87], v[16:17], v[250:251]
	v_pk_mul_f32 v[186:187], v[84:85], v[206:207]
	v_add_f32_e32 v0, v250, v251
	v_pk_fma_f32 v[110:111], v[86:87], v[12:13], v[110:111]
	v_pk_fma_f32 v[186:187], v[86:87], v[208:209], v[186:187]
	v_add_f32_dpp v0, v0, v0 row_ror:8 row_mask:0xf bank_mask:0xf bound_ctrl:1
	s_waitcnt lgkmcnt(6)
	v_pk_mul_f32 v[220:221], v[220:221], v[246:247] op_sel_hi:[1,0]
	v_add_f32_e32 v219, v186, v187
	v_add_f32_dpp v0, v0, v0 row_ror:4 row_mask:0xf bank_mask:0xf bound_ctrl:1
	v_pk_mul_f32 v[222:223], v[222:223], v[246:247] op_sel_hi:[1,0]
	ds_write2st64_b32 v77, v218, v219 offset0:24 offset1:28
	ds_read_b128 v[236:239], v53 offset:15552
	ds_read_b32 v234, v65 offset:16064
	ds_read_b128 v[198:201], v53 offset:15040
	v_add_f32_dpp v0, v0, v0 row_ror:2 row_mask:0xf bank_mask:0xf bound_ctrl:1
	ds_read_b128 v[194:197], v53 offset:14784
	ds_read_b128 v[202:205], v53 offset:15296
	ds_read_b128 v[206:209], v53 offset:15808
	v_add_f32_dpp v0, v0, v0 row_ror:1 row_mask:0xf bank_mask:0xf bound_ctrl:1
	v_pk_fma_f32 v[84:85], v[0:1], v[18:19], v[108:109] op_sel_hi:[0,1,1]
	v_pk_fma_f32 v[86:87], v[0:1], v[20:21], v[110:111] op_sel_hi:[0,1,1]
	v_pk_mul_f32 v[250:251], v[84:85], v[122:123]
	v_pk_fma_f32 v[220:221], v[84:85], v[118:119], v[220:221]
	v_pk_fma_f32 v[250:251], v[86:87], v[124:125], v[250:251]
	v_pk_mul_f32 v[186:187], v[84:85], v[22:23]
	v_add_f32_e32 v0, v250, v251
	v_pk_fma_f32 v[222:223], v[86:87], v[120:121], v[222:223]
	v_pk_fma_f32 v[186:187], v[86:87], v[24:25], v[186:187]
	v_add_f32_dpp v0, v0, v0 row_ror:8 row_mask:0xf bank_mask:0xf bound_ctrl:1
	s_waitcnt lgkmcnt(7)
	v_pk_mul_f32 v[224:225], v[224:225], v[214:215] op_sel_hi:[1,0]
	v_add_f32_e32 v218, v186, v187
	v_add_f32_dpp v0, v0, v0 row_ror:4 row_mask:0xf bank_mask:0xf bound_ctrl:1
	v_pk_mul_f32 v[226:227], v[226:227], v[214:215] op_sel_hi:[1,0]
	ds_read_b128 v[108:111], v53 offset:16896
	ds_read_b32 v242, v65 offset:17408
	ds_read_b128 v[14:17], v53 offset:16384
	v_add_f32_dpp v0, v0, v0 row_ror:2 row_mask:0xf bank_mask:0xf bound_ctrl:1
	ds_read_b128 v[10:13], v53 offset:16128
	ds_read_b128 v[18:21], v53 offset:16640
	ds_read_b128 v[22:25], v53 offset:17152
	v_add_f32_dpp v0, v0, v0 row_ror:1 row_mask:0xf bank_mask:0xf bound_ctrl:1
	v_pk_fma_f32 v[84:85], v[0:1], v[134:135], v[220:221] op_sel_hi:[0,1,1]
	v_pk_fma_f32 v[86:87], v[0:1], v[136:137], v[222:223] op_sel_hi:[0,1,1]
	v_pk_mul_f32 v[250:251], v[84:85], v[142:143]
	v_pk_fma_f32 v[224:225], v[84:85], v[138:139], v[224:225]
	v_pk_fma_f32 v[250:251], v[86:87], v[144:145], v[250:251]
	v_pk_mul_f32 v[186:187], v[84:85], v[230:231]
	v_add_f32_e32 v0, v250, v251
	v_pk_fma_f32 v[226:227], v[86:87], v[140:141], v[226:227]
	v_pk_fma_f32 v[186:187], v[86:87], v[232:233], v[186:187]
	v_add_f32_dpp v0, v0, v0 row_ror:8 row_mask:0xf bank_mask:0xf bound_ctrl:1
	s_waitcnt lgkmcnt(6)
	v_pk_mul_f32 v[236:237], v[236:237], v[234:235] op_sel_hi:[1,0]
	v_add_f32_e32 v219, v186, v187
	v_add_f32_dpp v0, v0, v0 row_ror:4 row_mask:0xf bank_mask:0xf bound_ctrl:1
	v_pk_mul_f32 v[238:239], v[238:239], v[234:235] op_sel_hi:[1,0]
	ds_write2st64_b32 v77, v218, v219 offset0:32 offset1:36
	ds_read_b128 v[220:223], v53 offset:18240
	ds_read_b32 v246, v65 offset:18752
	ds_read_b128 v[122:125], v53 offset:17728
	v_add_f32_dpp v0, v0, v0 row_ror:2 row_mask:0xf bank_mask:0xf bound_ctrl:1
	ds_read_b128 v[118:121], v53 offset:17472
	ds_read_b128 v[134:137], v53 offset:17984
	ds_read_b128 v[230:233], v53 offset:18496
	v_add_f32_dpp v0, v0, v0 row_ror:1 row_mask:0xf bank_mask:0xf bound_ctrl:1
	v_pk_fma_f32 v[84:85], v[0:1], v[146:147], v[224:225] op_sel_hi:[0,1,1]
	v_pk_fma_f32 v[86:87], v[0:1], v[148:149], v[226:227] op_sel_hi:[0,1,1]
	v_pk_mul_f32 v[250:251], v[84:85], v[198:199]
	v_pk_fma_f32 v[236:237], v[84:85], v[194:195], v[236:237]
	v_pk_fma_f32 v[250:251], v[86:87], v[200:201], v[250:251]
	v_pk_mul_f32 v[186:187], v[84:85], v[150:151]
	v_add_f32_e32 v0, v250, v251
	v_pk_fma_f32 v[238:239], v[86:87], v[196:197], v[238:239]
	v_pk_fma_f32 v[186:187], v[86:87], v[152:153], v[186:187]
	v_add_f32_dpp v0, v0, v0 row_ror:8 row_mask:0xf bank_mask:0xf bound_ctrl:1
	s_waitcnt lgkmcnt(7)
	v_pk_mul_f32 v[108:109], v[108:109], v[242:243] op_sel_hi:[1,0]
	v_add_f32_e32 v218, v186, v187
	v_add_f32_dpp v0, v0, v0 row_ror:4 row_mask:0xf bank_mask:0xf bound_ctrl:1
	v_pk_mul_f32 v[110:111], v[110:111], v[242:243] op_sel_hi:[1,0]
	ds_read_b128 v[224:227], v53 offset:19584
	ds_read_b32 v214, v65 offset:20096
	ds_read_b128 v[142:145], v53 offset:19072
	v_add_f32_dpp v0, v0, v0 row_ror:2 row_mask:0xf bank_mask:0xf bound_ctrl:1
	ds_read_b128 v[138:141], v53 offset:18816
	ds_read_b128 v[146:149], v53 offset:19328
	ds_read_b128 v[150:153], v53 offset:19840
	v_add_f32_dpp v0, v0, v0 row_ror:1 row_mask:0xf bank_mask:0xf bound_ctrl:1
	v_pk_fma_f32 v[84:85], v[0:1], v[202:203], v[236:237] op_sel_hi:[0,1,1]
	v_pk_fma_f32 v[86:87], v[0:1], v[204:205], v[238:239] op_sel_hi:[0,1,1]
	v_pk_mul_f32 v[250:251], v[84:85], v[14:15]
	v_pk_fma_f32 v[108:109], v[84:85], v[10:11], v[108:109]
	v_pk_fma_f32 v[250:251], v[86:87], v[16:17], v[250:251]
	v_pk_mul_f32 v[186:187], v[84:85], v[206:207]
	v_add_f32_e32 v0, v250, v251
	v_pk_fma_f32 v[110:111], v[86:87], v[12:13], v[110:111]
	v_pk_fma_f32 v[186:187], v[86:87], v[208:209], v[186:187]
	v_add_f32_dpp v0, v0, v0 row_ror:8 row_mask:0xf bank_mask:0xf bound_ctrl:1
	s_waitcnt lgkmcnt(6)
	v_pk_mul_f32 v[220:221], v[220:221], v[246:247] op_sel_hi:[1,0]
	v_add_f32_e32 v219, v186, v187
	v_add_f32_dpp v0, v0, v0 row_ror:4 row_mask:0xf bank_mask:0xf bound_ctrl:1
	v_pk_mul_f32 v[222:223], v[222:223], v[246:247] op_sel_hi:[1,0]
	ds_write2st64_b32 v77, v218, v219 offset0:40 offset1:44
	ds_read_b128 v[236:239], v53 offset:20928
	ds_read_b32 v234, v65 offset:21440
	ds_read_b128 v[198:201], v53 offset:20416
	v_add_f32_dpp v0, v0, v0 row_ror:2 row_mask:0xf bank_mask:0xf bound_ctrl:1
	ds_read_b128 v[194:197], v53 offset:20160
	ds_read_b128 v[202:205], v53 offset:20672
	ds_read_b128 v[206:209], v53 offset:21184
	v_add_f32_dpp v0, v0, v0 row_ror:1 row_mask:0xf bank_mask:0xf bound_ctrl:1
	v_pk_fma_f32 v[84:85], v[0:1], v[18:19], v[108:109] op_sel_hi:[0,1,1]
	v_pk_fma_f32 v[86:87], v[0:1], v[20:21], v[110:111] op_sel_hi:[0,1,1]
	v_pk_mul_f32 v[250:251], v[84:85], v[122:123]
	v_pk_fma_f32 v[220:221], v[84:85], v[118:119], v[220:221]
	v_pk_fma_f32 v[250:251], v[86:87], v[124:125], v[250:251]
	v_pk_mul_f32 v[186:187], v[84:85], v[22:23]
	v_add_f32_e32 v0, v250, v251
	v_pk_fma_f32 v[222:223], v[86:87], v[120:121], v[222:223]
	v_pk_fma_f32 v[186:187], v[86:87], v[24:25], v[186:187]
	v_add_f32_dpp v0, v0, v0 row_ror:8 row_mask:0xf bank_mask:0xf bound_ctrl:1
	s_waitcnt lgkmcnt(7)
	v_pk_mul_f32 v[224:225], v[224:225], v[214:215] op_sel_hi:[1,0]
	v_add_f32_e32 v218, v186, v187
	v_add_f32_dpp v0, v0, v0 row_ror:4 row_mask:0xf bank_mask:0xf bound_ctrl:1
	v_pk_mul_f32 v[226:227], v[226:227], v[214:215] op_sel_hi:[1,0]
	ds_read_b128 v[108:111], v53 offset:22272
	ds_read_b32 v242, v65 offset:22784
	ds_read_b128 v[14:17], v53 offset:21760
	v_add_f32_dpp v0, v0, v0 row_ror:2 row_mask:0xf bank_mask:0xf bound_ctrl:1
	ds_read_b128 v[10:13], v53 offset:21504
	ds_read_b128 v[18:21], v53 offset:22016
	ds_read_b128 v[22:25], v53 offset:22528
	v_add_f32_dpp v0, v0, v0 row_ror:1 row_mask:0xf bank_mask:0xf bound_ctrl:1
	v_pk_fma_f32 v[84:85], v[0:1], v[134:135], v[220:221] op_sel_hi:[0,1,1]
	v_pk_fma_f32 v[86:87], v[0:1], v[136:137], v[222:223] op_sel_hi:[0,1,1]
	v_pk_mul_f32 v[250:251], v[84:85], v[142:143]
	v_pk_fma_f32 v[224:225], v[84:85], v[138:139], v[224:225]
	v_pk_fma_f32 v[250:251], v[86:87], v[144:145], v[250:251]
	v_pk_mul_f32 v[186:187], v[84:85], v[230:231]
	v_add_f32_e32 v0, v250, v251
	v_pk_fma_f32 v[226:227], v[86:87], v[140:141], v[226:227]
	v_pk_fma_f32 v[186:187], v[86:87], v[232:233], v[186:187]
	v_add_f32_dpp v0, v0, v0 row_ror:8 row_mask:0xf bank_mask:0xf bound_ctrl:1
	s_waitcnt lgkmcnt(6)
	v_pk_mul_f32 v[236:237], v[236:237], v[234:235] op_sel_hi:[1,0]
	v_add_f32_e32 v219, v186, v187
	v_add_f32_dpp v0, v0, v0 row_ror:4 row_mask:0xf bank_mask:0xf bound_ctrl:1
	v_pk_mul_f32 v[238:239], v[238:239], v[234:235] op_sel_hi:[1,0]
	ds_write2st64_b32 v77, v218, v219 offset0:48 offset1:52
	ds_read_b128 v[220:223], v53 offset:23616
	ds_read_b32 v246, v65 offset:24128
	ds_read_b128 v[122:125], v53 offset:23104
	v_add_f32_dpp v0, v0, v0 row_ror:2 row_mask:0xf bank_mask:0xf bound_ctrl:1
	ds_read_b128 v[118:121], v53 offset:22848
	ds_read_b128 v[134:137], v53 offset:23360
	ds_read_b128 v[230:233], v53 offset:23872
	v_add_f32_dpp v0, v0, v0 row_ror:1 row_mask:0xf bank_mask:0xf bound_ctrl:1
	v_pk_fma_f32 v[84:85], v[0:1], v[146:147], v[224:225] op_sel_hi:[0,1,1]
	v_pk_fma_f32 v[86:87], v[0:1], v[148:149], v[226:227] op_sel_hi:[0,1,1]
	v_pk_mul_f32 v[250:251], v[84:85], v[198:199]
	v_pk_fma_f32 v[236:237], v[84:85], v[194:195], v[236:237]
	v_pk_fma_f32 v[250:251], v[86:87], v[200:201], v[250:251]
	v_pk_mul_f32 v[186:187], v[84:85], v[150:151]
	v_add_f32_e32 v0, v250, v251
	v_pk_fma_f32 v[238:239], v[86:87], v[196:197], v[238:239]
	v_pk_fma_f32 v[186:187], v[86:87], v[152:153], v[186:187]
	v_add_f32_dpp v0, v0, v0 row_ror:8 row_mask:0xf bank_mask:0xf bound_ctrl:1
	s_waitcnt lgkmcnt(7)
	v_pk_mul_f32 v[108:109], v[108:109], v[242:243] op_sel_hi:[1,0]
	v_add_f32_e32 v218, v186, v187
	v_add_f32_dpp v0, v0, v0 row_ror:4 row_mask:0xf bank_mask:0xf bound_ctrl:1
	v_pk_mul_f32 v[110:111], v[110:111], v[242:243] op_sel_hi:[1,0]
	ds_read_b128 v[224:227], v53 offset:24960
	ds_read_b32 v214, v65 offset:25472
	ds_read_b128 v[142:145], v53 offset:24448
	v_add_f32_dpp v0, v0, v0 row_ror:2 row_mask:0xf bank_mask:0xf bound_ctrl:1
	ds_read_b128 v[138:141], v53 offset:24192
	ds_read_b128 v[146:149], v53 offset:24704
	ds_read_b128 v[150:153], v53 offset:25216
	v_add_f32_dpp v0, v0, v0 row_ror:1 row_mask:0xf bank_mask:0xf bound_ctrl:1
	v_pk_fma_f32 v[84:85], v[0:1], v[202:203], v[236:237] op_sel_hi:[0,1,1]
	v_pk_fma_f32 v[86:87], v[0:1], v[204:205], v[238:239] op_sel_hi:[0,1,1]
	v_pk_mul_f32 v[250:251], v[84:85], v[14:15]
	v_pk_fma_f32 v[108:109], v[84:85], v[10:11], v[108:109]
	v_pk_fma_f32 v[250:251], v[86:87], v[16:17], v[250:251]
	v_pk_mul_f32 v[186:187], v[84:85], v[206:207]
	v_add_f32_e32 v0, v250, v251
	v_pk_fma_f32 v[110:111], v[86:87], v[12:13], v[110:111]
	v_pk_fma_f32 v[186:187], v[86:87], v[208:209], v[186:187]
	v_add_f32_dpp v0, v0, v0 row_ror:8 row_mask:0xf bank_mask:0xf bound_ctrl:1
	s_waitcnt lgkmcnt(6)
	v_pk_mul_f32 v[220:221], v[220:221], v[246:247] op_sel_hi:[1,0]
	v_add_f32_e32 v219, v186, v187
	v_add_f32_dpp v0, v0, v0 row_ror:4 row_mask:0xf bank_mask:0xf bound_ctrl:1
	v_pk_mul_f32 v[222:223], v[222:223], v[246:247] op_sel_hi:[1,0]
	ds_write2st64_b32 v77, v218, v219 offset0:56 offset1:60
	ds_read_b128 v[236:239], v53 offset:26304
	ds_read_b32 v234, v65 offset:26816
	ds_read_b128 v[198:201], v53 offset:25792
	v_add_f32_dpp v0, v0, v0 row_ror:2 row_mask:0xf bank_mask:0xf bound_ctrl:1
	ds_read_b128 v[194:197], v53 offset:25536
	ds_read_b128 v[202:205], v53 offset:26048
	ds_read_b128 v[206:209], v53 offset:26560
	v_add_f32_dpp v0, v0, v0 row_ror:1 row_mask:0xf bank_mask:0xf bound_ctrl:1
	v_pk_fma_f32 v[84:85], v[0:1], v[18:19], v[108:109] op_sel_hi:[0,1,1]
	v_pk_fma_f32 v[86:87], v[0:1], v[20:21], v[110:111] op_sel_hi:[0,1,1]
	v_pk_mul_f32 v[250:251], v[84:85], v[122:123]
	v_pk_fma_f32 v[220:221], v[84:85], v[118:119], v[220:221]
	v_pk_fma_f32 v[250:251], v[86:87], v[124:125], v[250:251]
	v_pk_mul_f32 v[186:187], v[84:85], v[22:23]
	v_add_f32_e32 v0, v250, v251
	v_pk_fma_f32 v[222:223], v[86:87], v[120:121], v[222:223]
	v_pk_fma_f32 v[186:187], v[86:87], v[24:25], v[186:187]
	v_add_f32_dpp v0, v0, v0 row_ror:8 row_mask:0xf bank_mask:0xf bound_ctrl:1
	s_waitcnt lgkmcnt(7)
	v_pk_mul_f32 v[224:225], v[224:225], v[214:215] op_sel_hi:[1,0]
	v_add_f32_e32 v218, v186, v187
	v_add_f32_dpp v0, v0, v0 row_ror:4 row_mask:0xf bank_mask:0xf bound_ctrl:1
	v_pk_mul_f32 v[226:227], v[226:227], v[214:215] op_sel_hi:[1,0]
	ds_read_b128 v[108:111], v53 offset:27648
	ds_read_b32 v242, v65 offset:28160
	ds_read_b128 v[14:17], v53 offset:27136
	v_add_f32_dpp v0, v0, v0 row_ror:2 row_mask:0xf bank_mask:0xf bound_ctrl:1
	ds_read_b128 v[10:13], v53 offset:26880
	ds_read_b128 v[18:21], v53 offset:27392
	ds_read_b128 v[22:25], v53 offset:27904
	v_add_f32_dpp v0, v0, v0 row_ror:1 row_mask:0xf bank_mask:0xf bound_ctrl:1
	v_pk_fma_f32 v[84:85], v[0:1], v[134:135], v[220:221] op_sel_hi:[0,1,1]
	v_pk_fma_f32 v[86:87], v[0:1], v[136:137], v[222:223] op_sel_hi:[0,1,1]
	v_pk_mul_f32 v[250:251], v[84:85], v[142:143]
	v_pk_fma_f32 v[224:225], v[84:85], v[138:139], v[224:225]
	v_pk_fma_f32 v[250:251], v[86:87], v[144:145], v[250:251]
	v_pk_mul_f32 v[186:187], v[84:85], v[230:231]
	v_add_f32_e32 v0, v250, v251
	v_pk_fma_f32 v[226:227], v[86:87], v[140:141], v[226:227]
	v_pk_fma_f32 v[186:187], v[86:87], v[232:233], v[186:187]
	v_add_f32_dpp v0, v0, v0 row_ror:8 row_mask:0xf bank_mask:0xf bound_ctrl:1
	s_waitcnt lgkmcnt(6)
	v_pk_mul_f32 v[236:237], v[236:237], v[234:235] op_sel_hi:[1,0]
	v_add_f32_e32 v219, v186, v187
	v_add_f32_dpp v0, v0, v0 row_ror:4 row_mask:0xf bank_mask:0xf bound_ctrl:1
	v_pk_mul_f32 v[238:239], v[238:239], v[234:235] op_sel_hi:[1,0]
	ds_write2st64_b32 v77, v218, v219 offset0:64 offset1:68
	ds_read_b128 v[220:223], v53 offset:28992
	ds_read_b32 v246, v65 offset:29504
	ds_read_b128 v[122:125], v53 offset:28480
	v_add_f32_dpp v0, v0, v0 row_ror:2 row_mask:0xf bank_mask:0xf bound_ctrl:1
	ds_read_b128 v[118:121], v53 offset:28224
	ds_read_b128 v[134:137], v53 offset:28736
	ds_read_b128 v[230:233], v53 offset:29248
	v_add_f32_dpp v0, v0, v0 row_ror:1 row_mask:0xf bank_mask:0xf bound_ctrl:1
	v_pk_fma_f32 v[84:85], v[0:1], v[146:147], v[224:225] op_sel_hi:[0,1,1]
	v_pk_fma_f32 v[86:87], v[0:1], v[148:149], v[226:227] op_sel_hi:[0,1,1]
	v_pk_mul_f32 v[250:251], v[84:85], v[198:199]
	v_pk_fma_f32 v[236:237], v[84:85], v[194:195], v[236:237]
	v_pk_fma_f32 v[250:251], v[86:87], v[200:201], v[250:251]
	v_pk_mul_f32 v[186:187], v[84:85], v[150:151]
	v_add_f32_e32 v0, v250, v251
	v_pk_fma_f32 v[238:239], v[86:87], v[196:197], v[238:239]
	v_pk_fma_f32 v[186:187], v[86:87], v[152:153], v[186:187]
	v_add_f32_dpp v0, v0, v0 row_ror:8 row_mask:0xf bank_mask:0xf bound_ctrl:1
	s_waitcnt lgkmcnt(7)
	v_pk_mul_f32 v[108:109], v[108:109], v[242:243] op_sel_hi:[1,0]
	v_add_f32_e32 v218, v186, v187
	v_add_f32_dpp v0, v0, v0 row_ror:4 row_mask:0xf bank_mask:0xf bound_ctrl:1
	v_pk_mul_f32 v[110:111], v[110:111], v[242:243] op_sel_hi:[1,0]
	ds_read_b128 v[224:227], v53 offset:30336
	ds_read_b32 v214, v65 offset:30848
	ds_read_b128 v[142:145], v53 offset:29824
	v_add_f32_dpp v0, v0, v0 row_ror:2 row_mask:0xf bank_mask:0xf bound_ctrl:1
	ds_read_b128 v[138:141], v53 offset:29568
	ds_read_b128 v[146:149], v53 offset:30080
	ds_read_b128 v[150:153], v53 offset:30592
	v_add_f32_dpp v0, v0, v0 row_ror:1 row_mask:0xf bank_mask:0xf bound_ctrl:1
	v_pk_fma_f32 v[84:85], v[0:1], v[202:203], v[236:237] op_sel_hi:[0,1,1]
	v_pk_fma_f32 v[86:87], v[0:1], v[204:205], v[238:239] op_sel_hi:[0,1,1]
	v_pk_mul_f32 v[250:251], v[84:85], v[14:15]
	v_pk_fma_f32 v[108:109], v[84:85], v[10:11], v[108:109]
	v_pk_fma_f32 v[250:251], v[86:87], v[16:17], v[250:251]
	v_pk_mul_f32 v[186:187], v[84:85], v[206:207]
	v_add_f32_e32 v0, v250, v251
	v_pk_fma_f32 v[110:111], v[86:87], v[12:13], v[110:111]
	v_pk_fma_f32 v[186:187], v[86:87], v[208:209], v[186:187]
	v_add_f32_dpp v0, v0, v0 row_ror:8 row_mask:0xf bank_mask:0xf bound_ctrl:1
	s_waitcnt lgkmcnt(6)
	v_pk_mul_f32 v[220:221], v[220:221], v[246:247] op_sel_hi:[1,0]
	v_add_f32_e32 v219, v186, v187
	v_add_f32_dpp v0, v0, v0 row_ror:4 row_mask:0xf bank_mask:0xf bound_ctrl:1
	v_pk_mul_f32 v[222:223], v[222:223], v[246:247] op_sel_hi:[1,0]
	ds_write2st64_b32 v77, v218, v219 offset0:72 offset1:76
	ds_read_b128 v[236:239], v53 offset:31680
	ds_read_b32 v234, v65 offset:32192
	ds_read_b128 v[198:201], v53 offset:31168
	v_add_f32_dpp v0, v0, v0 row_ror:2 row_mask:0xf bank_mask:0xf bound_ctrl:1
	ds_read_b128 v[194:197], v53 offset:30912
	ds_read_b128 v[202:205], v53 offset:31424
	ds_read_b128 v[206:209], v53 offset:31936
	v_add_f32_dpp v0, v0, v0 row_ror:1 row_mask:0xf bank_mask:0xf bound_ctrl:1
	v_pk_fma_f32 v[84:85], v[0:1], v[18:19], v[108:109] op_sel_hi:[0,1,1]
	v_pk_fma_f32 v[86:87], v[0:1], v[20:21], v[110:111] op_sel_hi:[0,1,1]
	v_pk_mul_f32 v[250:251], v[84:85], v[122:123]
	v_pk_fma_f32 v[220:221], v[84:85], v[118:119], v[220:221]
	v_pk_fma_f32 v[250:251], v[86:87], v[124:125], v[250:251]
	v_pk_mul_f32 v[186:187], v[84:85], v[22:23]
	v_add_f32_e32 v0, v250, v251
	v_pk_fma_f32 v[222:223], v[86:87], v[120:121], v[222:223]
	v_pk_fma_f32 v[186:187], v[86:87], v[24:25], v[186:187]
	v_add_f32_dpp v0, v0, v0 row_ror:8 row_mask:0xf bank_mask:0xf bound_ctrl:1
	s_waitcnt lgkmcnt(7)
	v_pk_mul_f32 v[224:225], v[224:225], v[214:215] op_sel_hi:[1,0]
	v_add_f32_e32 v218, v186, v187
	v_add_f32_dpp v0, v0, v0 row_ror:4 row_mask:0xf bank_mask:0xf bound_ctrl:1
	v_pk_mul_f32 v[226:227], v[226:227], v[214:215] op_sel_hi:[1,0]
	ds_read_b128 v[108:111], v53 offset:33024
	ds_read_b32 v242, v65 offset:33536
	ds_read_b128 v[14:17], v53 offset:32512
	v_add_f32_dpp v0, v0, v0 row_ror:2 row_mask:0xf bank_mask:0xf bound_ctrl:1
	ds_read_b128 v[10:13], v53 offset:32256
	ds_read_b128 v[18:21], v53 offset:32768
	ds_read_b128 v[22:25], v53 offset:33280
	v_add_f32_dpp v0, v0, v0 row_ror:1 row_mask:0xf bank_mask:0xf bound_ctrl:1
	v_pk_fma_f32 v[84:85], v[0:1], v[134:135], v[220:221] op_sel_hi:[0,1,1]
	v_pk_fma_f32 v[86:87], v[0:1], v[136:137], v[222:223] op_sel_hi:[0,1,1]
	v_pk_mul_f32 v[250:251], v[84:85], v[142:143]
	v_pk_fma_f32 v[224:225], v[84:85], v[138:139], v[224:225]
	v_pk_fma_f32 v[250:251], v[86:87], v[144:145], v[250:251]
	v_pk_mul_f32 v[186:187], v[84:85], v[230:231]
	v_add_f32_e32 v0, v250, v251
	v_pk_fma_f32 v[226:227], v[86:87], v[140:141], v[226:227]
	v_pk_fma_f32 v[186:187], v[86:87], v[232:233], v[186:187]
	v_add_f32_dpp v0, v0, v0 row_ror:8 row_mask:0xf bank_mask:0xf bound_ctrl:1
	s_waitcnt lgkmcnt(6)
	v_pk_mul_f32 v[236:237], v[236:237], v[234:235] op_sel_hi:[1,0]
	v_add_f32_e32 v219, v186, v187
	v_add_f32_dpp v0, v0, v0 row_ror:4 row_mask:0xf bank_mask:0xf bound_ctrl:1
	v_pk_mul_f32 v[238:239], v[238:239], v[234:235] op_sel_hi:[1,0]
	ds_write2st64_b32 v77, v218, v219 offset0:80 offset1:84
	ds_read_b128 v[220:223], v53 offset:34368
	ds_read_b32 v246, v65 offset:34880
	ds_read_b128 v[122:125], v53 offset:33856
	v_add_f32_dpp v0, v0, v0 row_ror:2 row_mask:0xf bank_mask:0xf bound_ctrl:1
	ds_read_b128 v[118:121], v53 offset:33600
	ds_read_b128 v[134:137], v53 offset:34112
	ds_read_b128 v[230:233], v53 offset:34624
	v_add_f32_dpp v0, v0, v0 row_ror:1 row_mask:0xf bank_mask:0xf bound_ctrl:1
	v_pk_fma_f32 v[84:85], v[0:1], v[146:147], v[224:225] op_sel_hi:[0,1,1]
	v_pk_fma_f32 v[86:87], v[0:1], v[148:149], v[226:227] op_sel_hi:[0,1,1]
	v_pk_mul_f32 v[250:251], v[84:85], v[198:199]
	v_pk_fma_f32 v[236:237], v[84:85], v[194:195], v[236:237]
	v_pk_fma_f32 v[250:251], v[86:87], v[200:201], v[250:251]
	v_pk_mul_f32 v[186:187], v[84:85], v[150:151]
	v_add_f32_e32 v0, v250, v251
	v_pk_fma_f32 v[238:239], v[86:87], v[196:197], v[238:239]
	v_pk_fma_f32 v[186:187], v[86:87], v[152:153], v[186:187]
	v_add_f32_dpp v0, v0, v0 row_ror:8 row_mask:0xf bank_mask:0xf bound_ctrl:1
	s_waitcnt lgkmcnt(7)
	v_pk_mul_f32 v[108:109], v[108:109], v[242:243] op_sel_hi:[1,0]
	v_add_f32_e32 v218, v186, v187
	v_add_f32_dpp v0, v0, v0 row_ror:4 row_mask:0xf bank_mask:0xf bound_ctrl:1
	v_pk_mul_f32 v[110:111], v[110:111], v[242:243] op_sel_hi:[1,0]
	ds_read_b128 v[224:227], v53 offset:35712
	ds_read_b32 v214, v65 offset:36224
	ds_read_b128 v[142:145], v53 offset:35200
	v_add_f32_dpp v0, v0, v0 row_ror:2 row_mask:0xf bank_mask:0xf bound_ctrl:1
	ds_read_b128 v[138:141], v53 offset:34944
	ds_read_b128 v[146:149], v53 offset:35456
	ds_read_b128 v[150:153], v53 offset:35968
	v_add_f32_dpp v0, v0, v0 row_ror:1 row_mask:0xf bank_mask:0xf bound_ctrl:1
	v_pk_fma_f32 v[84:85], v[0:1], v[202:203], v[236:237] op_sel_hi:[0,1,1]
	v_pk_fma_f32 v[86:87], v[0:1], v[204:205], v[238:239] op_sel_hi:[0,1,1]
	v_pk_mul_f32 v[250:251], v[84:85], v[14:15]
	v_pk_fma_f32 v[108:109], v[84:85], v[10:11], v[108:109]
	v_pk_fma_f32 v[250:251], v[86:87], v[16:17], v[250:251]
	v_pk_mul_f32 v[186:187], v[84:85], v[206:207]
	v_add_f32_e32 v0, v250, v251
	v_pk_fma_f32 v[110:111], v[86:87], v[12:13], v[110:111]
	v_pk_fma_f32 v[186:187], v[86:87], v[208:209], v[186:187]
	v_add_f32_dpp v0, v0, v0 row_ror:8 row_mask:0xf bank_mask:0xf bound_ctrl:1
	s_waitcnt lgkmcnt(6)
	v_pk_mul_f32 v[220:221], v[220:221], v[246:247] op_sel_hi:[1,0]
	v_add_f32_e32 v219, v186, v187
	v_add_f32_dpp v0, v0, v0 row_ror:4 row_mask:0xf bank_mask:0xf bound_ctrl:1
	v_pk_mul_f32 v[222:223], v[222:223], v[246:247] op_sel_hi:[1,0]
	ds_write2st64_b32 v77, v218, v219 offset0:88 offset1:92
	ds_read_b128 v[236:239], v53 offset:37056
	ds_read_b32 v234, v65 offset:37568
	ds_read_b128 v[198:201], v53 offset:36544
	v_add_f32_dpp v0, v0, v0 row_ror:2 row_mask:0xf bank_mask:0xf bound_ctrl:1
	ds_read_b128 v[194:197], v53 offset:36288
	ds_read_b128 v[202:205], v53 offset:36800
	ds_read_b128 v[206:209], v53 offset:37312
	v_add_f32_dpp v0, v0, v0 row_ror:1 row_mask:0xf bank_mask:0xf bound_ctrl:1
	v_pk_fma_f32 v[84:85], v[0:1], v[18:19], v[108:109] op_sel_hi:[0,1,1]
	v_pk_fma_f32 v[86:87], v[0:1], v[20:21], v[110:111] op_sel_hi:[0,1,1]
	v_pk_mul_f32 v[250:251], v[84:85], v[122:123]
	v_pk_fma_f32 v[220:221], v[84:85], v[118:119], v[220:221]
	v_pk_fma_f32 v[250:251], v[86:87], v[124:125], v[250:251]
	v_pk_mul_f32 v[186:187], v[84:85], v[22:23]
	v_add_f32_e32 v0, v250, v251
	v_pk_fma_f32 v[222:223], v[86:87], v[120:121], v[222:223]
	v_pk_fma_f32 v[186:187], v[86:87], v[24:25], v[186:187]
	v_add_f32_dpp v0, v0, v0 row_ror:8 row_mask:0xf bank_mask:0xf bound_ctrl:1
	s_waitcnt lgkmcnt(7)
	v_pk_mul_f32 v[224:225], v[224:225], v[214:215] op_sel_hi:[1,0]
	v_add_f32_e32 v218, v186, v187
	v_add_f32_dpp v0, v0, v0 row_ror:4 row_mask:0xf bank_mask:0xf bound_ctrl:1
	v_pk_mul_f32 v[226:227], v[226:227], v[214:215] op_sel_hi:[1,0]
	ds_read_b128 v[108:111], v53 offset:38400
	ds_read_b32 v242, v65 offset:38912
	ds_read_b128 v[14:17], v53 offset:37888
	v_add_f32_dpp v0, v0, v0 row_ror:2 row_mask:0xf bank_mask:0xf bound_ctrl:1
	ds_read_b128 v[10:13], v53 offset:37632
	ds_read_b128 v[18:21], v53 offset:38144
	ds_read_b128 v[22:25], v53 offset:38656
	v_add_f32_dpp v0, v0, v0 row_ror:1 row_mask:0xf bank_mask:0xf bound_ctrl:1
	v_pk_fma_f32 v[84:85], v[0:1], v[134:135], v[220:221] op_sel_hi:[0,1,1]
	v_pk_fma_f32 v[86:87], v[0:1], v[136:137], v[222:223] op_sel_hi:[0,1,1]
	v_pk_mul_f32 v[250:251], v[84:85], v[142:143]
	v_pk_fma_f32 v[224:225], v[84:85], v[138:139], v[224:225]
	v_pk_fma_f32 v[250:251], v[86:87], v[144:145], v[250:251]
	v_pk_mul_f32 v[186:187], v[84:85], v[230:231]
	v_add_f32_e32 v0, v250, v251
	v_pk_fma_f32 v[226:227], v[86:87], v[140:141], v[226:227]
	v_pk_fma_f32 v[186:187], v[86:87], v[232:233], v[186:187]
	v_add_f32_dpp v0, v0, v0 row_ror:8 row_mask:0xf bank_mask:0xf bound_ctrl:1
	s_waitcnt lgkmcnt(6)
	v_pk_mul_f32 v[236:237], v[236:237], v[234:235] op_sel_hi:[1,0]
	v_add_f32_e32 v219, v186, v187
	v_add_f32_dpp v0, v0, v0 row_ror:4 row_mask:0xf bank_mask:0xf bound_ctrl:1
	v_pk_mul_f32 v[238:239], v[238:239], v[234:235] op_sel_hi:[1,0]
	ds_write2st64_b32 v77, v218, v219 offset0:96 offset1:100
	ds_read_b128 v[220:223], v53 offset:39744
	ds_read_b32 v246, v65 offset:40256
	ds_read_b128 v[122:125], v53 offset:39232
	v_add_f32_dpp v0, v0, v0 row_ror:2 row_mask:0xf bank_mask:0xf bound_ctrl:1
	ds_read_b128 v[118:121], v53 offset:38976
	ds_read_b128 v[134:137], v53 offset:39488
	ds_read_b128 v[230:233], v53 offset:40000
	v_add_f32_dpp v0, v0, v0 row_ror:1 row_mask:0xf bank_mask:0xf bound_ctrl:1
	v_pk_fma_f32 v[84:85], v[0:1], v[146:147], v[224:225] op_sel_hi:[0,1,1]
	v_pk_fma_f32 v[86:87], v[0:1], v[148:149], v[226:227] op_sel_hi:[0,1,1]
	v_pk_mul_f32 v[250:251], v[84:85], v[198:199]
	v_pk_fma_f32 v[236:237], v[84:85], v[194:195], v[236:237]
	v_pk_fma_f32 v[250:251], v[86:87], v[200:201], v[250:251]
	v_pk_mul_f32 v[186:187], v[84:85], v[150:151]
	v_add_f32_e32 v0, v250, v251
	v_pk_fma_f32 v[238:239], v[86:87], v[196:197], v[238:239]
	v_pk_fma_f32 v[186:187], v[86:87], v[152:153], v[186:187]
	v_add_f32_dpp v0, v0, v0 row_ror:8 row_mask:0xf bank_mask:0xf bound_ctrl:1
	s_waitcnt lgkmcnt(7)
	v_pk_mul_f32 v[108:109], v[108:109], v[242:243] op_sel_hi:[1,0]
	v_add_f32_e32 v218, v186, v187
	v_add_f32_dpp v0, v0, v0 row_ror:4 row_mask:0xf bank_mask:0xf bound_ctrl:1
	v_pk_mul_f32 v[110:111], v[110:111], v[242:243] op_sel_hi:[1,0]
	ds_read_b128 v[224:227], v53 offset:41088
	ds_read_b32 v214, v65 offset:41600
	ds_read_b128 v[142:145], v53 offset:40576
	v_add_f32_dpp v0, v0, v0 row_ror:2 row_mask:0xf bank_mask:0xf bound_ctrl:1
	ds_read_b128 v[138:141], v53 offset:40320
	ds_read_b128 v[146:149], v53 offset:40832
	ds_read_b128 v[150:153], v53 offset:41344
	v_add_f32_dpp v0, v0, v0 row_ror:1 row_mask:0xf bank_mask:0xf bound_ctrl:1
	v_pk_fma_f32 v[84:85], v[0:1], v[202:203], v[236:237] op_sel_hi:[0,1,1]
	v_pk_fma_f32 v[86:87], v[0:1], v[204:205], v[238:239] op_sel_hi:[0,1,1]
	v_pk_mul_f32 v[250:251], v[84:85], v[14:15]
	v_pk_fma_f32 v[108:109], v[84:85], v[10:11], v[108:109]
	v_pk_fma_f32 v[250:251], v[86:87], v[16:17], v[250:251]
	v_pk_mul_f32 v[186:187], v[84:85], v[206:207]
	v_add_f32_e32 v0, v250, v251
	v_pk_fma_f32 v[110:111], v[86:87], v[12:13], v[110:111]
	v_pk_fma_f32 v[186:187], v[86:87], v[208:209], v[186:187]
	v_add_f32_dpp v0, v0, v0 row_ror:8 row_mask:0xf bank_mask:0xf bound_ctrl:1
	s_waitcnt lgkmcnt(6)
	v_pk_mul_f32 v[220:221], v[220:221], v[246:247] op_sel_hi:[1,0]
	v_add_f32_e32 v219, v186, v187
	v_add_f32_dpp v0, v0, v0 row_ror:4 row_mask:0xf bank_mask:0xf bound_ctrl:1
	v_pk_mul_f32 v[222:223], v[222:223], v[246:247] op_sel_hi:[1,0]
	ds_write2st64_b32 v77, v218, v219 offset0:104 offset1:108
	ds_read_b128 v[236:239], v53 offset:42432
	ds_read_b32 v234, v65 offset:42944
	ds_read_b128 v[198:201], v53 offset:41920
	v_add_f32_dpp v0, v0, v0 row_ror:2 row_mask:0xf bank_mask:0xf bound_ctrl:1
	ds_read_b128 v[194:197], v53 offset:41664
	ds_read_b128 v[202:205], v53 offset:42176
	ds_read_b128 v[206:209], v53 offset:42688
	v_add_f32_dpp v0, v0, v0 row_ror:1 row_mask:0xf bank_mask:0xf bound_ctrl:1
	v_pk_fma_f32 v[84:85], v[0:1], v[18:19], v[108:109] op_sel_hi:[0,1,1]
	v_pk_fma_f32 v[86:87], v[0:1], v[20:21], v[110:111] op_sel_hi:[0,1,1]
	v_pk_mul_f32 v[250:251], v[84:85], v[122:123]
	v_pk_fma_f32 v[220:221], v[84:85], v[118:119], v[220:221]
	v_pk_fma_f32 v[250:251], v[86:87], v[124:125], v[250:251]
	v_pk_mul_f32 v[186:187], v[84:85], v[22:23]
	v_add_f32_e32 v0, v250, v251
	v_pk_fma_f32 v[222:223], v[86:87], v[120:121], v[222:223]
	v_pk_fma_f32 v[186:187], v[86:87], v[24:25], v[186:187]
	v_add_f32_dpp v0, v0, v0 row_ror:8 row_mask:0xf bank_mask:0xf bound_ctrl:1
	s_waitcnt lgkmcnt(7)
	v_pk_mul_f32 v[224:225], v[224:225], v[214:215] op_sel_hi:[1,0]
	v_add_f32_e32 v218, v186, v187
	v_add_f32_dpp v0, v0, v0 row_ror:4 row_mask:0xf bank_mask:0xf bound_ctrl:1
	v_pk_mul_f32 v[226:227], v[226:227], v[214:215] op_sel_hi:[1,0]
	s_nop 0
	v_add_f32_dpp v0, v0, v0 row_ror:2 row_mask:0xf bank_mask:0xf bound_ctrl:1
	s_nop 1
	v_add_f32_dpp v0, v0, v0 row_ror:1 row_mask:0xf bank_mask:0xf bound_ctrl:1
	v_pk_fma_f32 v[84:85], v[0:1], v[134:135], v[220:221] op_sel_hi:[0,1,1]
	v_pk_fma_f32 v[86:87], v[0:1], v[136:137], v[222:223] op_sel_hi:[0,1,1]
	v_pk_mul_f32 v[250:251], v[84:85], v[142:143]
	v_pk_fma_f32 v[224:225], v[84:85], v[138:139], v[224:225]
	v_pk_fma_f32 v[250:251], v[86:87], v[144:145], v[250:251]
	v_pk_mul_f32 v[186:187], v[84:85], v[230:231]
	v_add_f32_e32 v0, v250, v251
	v_pk_fma_f32 v[226:227], v[86:87], v[140:141], v[226:227]
	v_pk_fma_f32 v[186:187], v[86:87], v[232:233], v[186:187]
	v_add_f32_dpp v0, v0, v0 row_ror:8 row_mask:0xf bank_mask:0xf bound_ctrl:1
	s_waitcnt lgkmcnt(0)
	v_pk_mul_f32 v[236:237], v[236:237], v[234:235] op_sel_hi:[1,0]
	v_add_f32_e32 v219, v186, v187
	v_add_f32_dpp v0, v0, v0 row_ror:4 row_mask:0xf bank_mask:0xf bound_ctrl:1
	v_pk_mul_f32 v[238:239], v[238:239], v[234:235] op_sel_hi:[1,0]
	ds_write2st64_b32 v77, v218, v219 offset0:112 offset1:116
	v_add_f32_dpp v0, v0, v0 row_ror:2 row_mask:0xf bank_mask:0xf bound_ctrl:1
	s_nop 1
	v_add_f32_dpp v0, v0, v0 row_ror:1 row_mask:0xf bank_mask:0xf bound_ctrl:1
	v_pk_fma_f32 v[84:85], v[0:1], v[146:147], v[224:225] op_sel_hi:[0,1,1]
	v_pk_fma_f32 v[86:87], v[0:1], v[148:149], v[226:227] op_sel_hi:[0,1,1]
	v_pk_mul_f32 v[250:251], v[84:85], v[198:199]
	v_pk_fma_f32 v[236:237], v[84:85], v[194:195], v[236:237]
	v_pk_fma_f32 v[250:251], v[86:87], v[200:201], v[250:251]
	v_pk_mul_f32 v[186:187], v[84:85], v[150:151]
	v_add_f32_e32 v0, v250, v251
	v_pk_fma_f32 v[238:239], v[86:87], v[196:197], v[238:239]
	v_pk_fma_f32 v[186:187], v[86:87], v[152:153], v[186:187]
	v_add_f32_dpp v0, v0, v0 row_ror:8 row_mask:0xf bank_mask:0xf bound_ctrl:1
	v_add_f32_e32 v218, v186, v187
	s_nop 0
	v_add_f32_dpp v0, v0, v0 row_ror:4 row_mask:0xf bank_mask:0xf bound_ctrl:1
	s_nop 1
	v_add_f32_dpp v0, v0, v0 row_ror:2 row_mask:0xf bank_mask:0xf bound_ctrl:1
	s_nop 1
	v_add_f32_dpp v0, v0, v0 row_ror:1 row_mask:0xf bank_mask:0xf bound_ctrl:1
	v_pk_fma_f32 v[84:85], v[0:1], v[202:203], v[236:237] op_sel_hi:[0,1,1]
	v_pk_fma_f32 v[86:87], v[0:1], v[204:205], v[238:239] op_sel_hi:[0,1,1]
	v_pk_mul_f32 v[186:187], v[84:85], v[206:207]
	s_nop 0
	v_pk_fma_f32 v[186:187], v[86:87], v[208:209], v[186:187]
	s_nop 0
	v_add_f32_e32 v219, v186, v187
	ds_write2st64_b32 v77, v218, v219 offset0:120 offset1:124

.LBB0_647:
	s_or_b64 exec, exec, s[34:35]
	s_waitcnt lgkmcnt(0)
	s_barrier
	s_and_saveexec_b64 s[34:35], s[2:3]
	s_xor_b64 s[50:51], exec, s[34:35]
	s_cbranch_execz .LBB0_650
	s_and_b64 vcc, exec, s[8:9]
	s_cbranch_vccnz .LBB0_650
	ds_read_b128 v[108:111], v96 offset:768
	ds_read_b32 v242, v97
	ds_read_b128 v[14:17], v96 offset:256
	ds_read_b128 v[10:13], v96
	ds_read_b128 v[18:21], v96 offset:512
	ds_read_b128 v[22:25], v96 offset:1024
	ds_read_b128 v[220:223], v96 offset:2112
	ds_read_b32 v246, v97 offset:1344
	ds_read_b128 v[122:125], v96 offset:1600
	ds_read_b128 v[118:121], v96 offset:1344
	ds_read_b128 v[134:137], v96 offset:1856
	ds_read_b128 v[230:233], v96 offset:2368
	ds_read_b128 v[224:227], v96 offset:3456
	ds_read_b32 v214, v97 offset:2688
	ds_read_b128 v[142:145], v96 offset:2944
	ds_read_b128 v[138:141], v96 offset:2688
	ds_read_b128 v[146:149], v96 offset:3200
	ds_read_b128 v[150:153], v96 offset:3712
	s_waitcnt lgkmcnt(12)
	v_pk_mul_f32 v[108:109], v[108:109], v[242:243] op_sel_hi:[1,0]
	v_pk_mul_f32 v[110:111], v[110:111], v[242:243] op_sel_hi:[1,0]
	v_pk_mul_f32 v[250:251], v[84:85], v[14:15]
	v_pk_fma_f32 v[108:109], v[84:85], v[10:11], v[108:109]
	v_pk_fma_f32 v[250:251], v[86:87], v[16:17], v[250:251]
	s_nop 0
	v_add_f32_e32 v0, v250, v251
	v_pk_fma_f32 v[110:111], v[86:87], v[12:13], v[110:111]
	s_nop 0
	v_add_f32_dpp v0, v0, v0 row_ror:8 row_mask:0xf bank_mask:0xf bound_ctrl:1
	s_waitcnt lgkmcnt(0)
	v_pk_mul_f32 v[220:221], v[220:221], v[246:247] op_sel_hi:[1,0]
	v_add_f32_dpp v0, v0, v0 row_ror:4 row_mask:0xf bank_mask:0xf bound_ctrl:1
	v_pk_mul_f32 v[222:223], v[222:223], v[246:247] op_sel_hi:[1,0]
	ds_read_b128 v[236:239], v96 offset:4800
	ds_read_b32 v234, v97 offset:4032
	ds_read_b128 v[198:201], v96 offset:4288
	v_add_f32_dpp v0, v0, v0 row_ror:2 row_mask:0xf bank_mask:0xf bound_ctrl:1
	ds_read_b128 v[194:197], v96 offset:4032
	ds_read_b128 v[202:205], v96 offset:4544
	ds_read_b128 v[206:209], v96 offset:5056
	v_add_f32_dpp v0, v0, v0 row_ror:1 row_mask:0xf bank_mask:0xf bound_ctrl:1
	v_pk_fma_f32 v[84:85], v[0:1], v[18:19], v[108:109] op_sel_hi:[0,1,1]
	v_pk_fma_f32 v[86:87], v[0:1], v[20:21], v[110:111] op_sel_hi:[0,1,1]
	v_pk_mul_f32 v[250:251], v[84:85], v[122:123]
	v_pk_fma_f32 v[220:221], v[84:85], v[118:119], v[220:221]
	v_pk_fma_f32 v[250:251], v[86:87], v[124:125], v[250:251]
	v_pk_mul_f32 v[186:187], v[84:85], v[22:23]
	v_add_f32_e32 v0, v250, v251
	v_pk_fma_f32 v[222:223], v[86:87], v[120:121], v[222:223]
	v_pk_fma_f32 v[186:187], v[86:87], v[24:25], v[186:187]
	v_add_f32_dpp v0, v0, v0 row_ror:8 row_mask:0xf bank_mask:0xf bound_ctrl:1
	s_waitcnt lgkmcnt(6)
	v_pk_mul_f32 v[224:225], v[224:225], v[214:215] op_sel_hi:[1,0]
	v_add_f32_e32 v218, v186, v187
	v_add_f32_dpp v0, v0, v0 row_ror:4 row_mask:0xf bank_mask:0xf bound_ctrl:1
	v_pk_mul_f32 v[226:227], v[226:227], v[214:215] op_sel_hi:[1,0]
	ds_read_b128 v[108:111], v96 offset:6144
	ds_read_b32 v242, v97 offset:5376
	ds_read_b128 v[14:17], v96 offset:5632
	v_add_f32_dpp v0, v0, v0 row_ror:2 row_mask:0xf bank_mask:0xf bound_ctrl:1
	ds_read_b128 v[10:13], v96 offset:5376
	ds_read_b128 v[18:21], v96 offset:5888
	ds_read_b128 v[22:25], v96 offset:6400
	v_add_f32_dpp v0, v0, v0 row_ror:1 row_mask:0xf bank_mask:0xf bound_ctrl:1
	v_pk_fma_f32 v[84:85], v[0:1], v[134:135], v[220:221] op_sel_hi:[0,1,1]
	v_pk_fma_f32 v[86:87], v[0:1], v[136:137], v[222:223] op_sel_hi:[0,1,1]
	v_pk_mul_f32 v[250:251], v[84:85], v[142:143]
	v_pk_fma_f32 v[224:225], v[84:85], v[138:139], v[224:225]
	v_pk_fma_f32 v[250:251], v[86:87], v[144:145], v[250:251]
	v_pk_mul_f32 v[186:187], v[84:85], v[230:231]
	v_add_f32_e32 v0, v250, v251
	v_pk_fma_f32 v[226:227], v[86:87], v[140:141], v[226:227]
	v_pk_fma_f32 v[186:187], v[86:87], v[232:233], v[186:187]
	v_add_f32_dpp v0, v0, v0 row_ror:8 row_mask:0xf bank_mask:0xf bound_ctrl:1
	s_waitcnt lgkmcnt(6)
	v_pk_mul_f32 v[236:237], v[236:237], v[234:235] op_sel_hi:[1,0]
	v_add_f32_e32 v219, v186, v187
	v_add_f32_dpp v0, v0, v0 row_ror:4 row_mask:0xf bank_mask:0xf bound_ctrl:1
	v_pk_mul_f32 v[238:239], v[238:239], v[234:235] op_sel_hi:[1,0]
	ds_write2st64_b32 v98, v218, v219 offset0:0 offset1:4
	ds_read_b128 v[220:223], v96 offset:7488
	ds_read_b32 v246, v97 offset:6720
	ds_read_b128 v[122:125], v96 offset:6976
	v_add_f32_dpp v0, v0, v0 row_ror:2 row_mask:0xf bank_mask:0xf bound_ctrl:1
	ds_read_b128 v[118:121], v96 offset:6720
	ds_read_b128 v[134:137], v96 offset:7232
	ds_read_b128 v[230:233], v96 offset:7744
	v_add_f32_dpp v0, v0, v0 row_ror:1 row_mask:0xf bank_mask:0xf bound_ctrl:1
	v_pk_fma_f32 v[84:85], v[0:1], v[146:147], v[224:225] op_sel_hi:[0,1,1]
	v_pk_fma_f32 v[86:87], v[0:1], v[148:149], v[226:227] op_sel_hi:[0,1,1]
	v_pk_mul_f32 v[250:251], v[84:85], v[198:199]
	v_pk_fma_f32 v[236:237], v[84:85], v[194:195], v[236:237]
	v_pk_fma_f32 v[250:251], v[86:87], v[200:201], v[250:251]
	v_pk_mul_f32 v[186:187], v[84:85], v[150:151]
	v_add_f32_e32 v0, v250, v251
	v_pk_fma_f32 v[238:239], v[86:87], v[196:197], v[238:239]
	v_pk_fma_f32 v[186:187], v[86:87], v[152:153], v[186:187]
	v_add_f32_dpp v0, v0, v0 row_ror:8 row_mask:0xf bank_mask:0xf bound_ctrl:1
	s_waitcnt lgkmcnt(7)
	v_pk_mul_f32 v[108:109], v[108:109], v[242:243] op_sel_hi:[1,0]
	v_add_f32_e32 v218, v186, v187
	v_add_f32_dpp v0, v0, v0 row_ror:4 row_mask:0xf bank_mask:0xf bound_ctrl:1
	v_pk_mul_f32 v[110:111], v[110:111], v[242:243] op_sel_hi:[1,0]
	ds_read_b128 v[224:227], v96 offset:8832
	ds_read_b32 v214, v97 offset:8064
	ds_read_b128 v[142:145], v96 offset:8320
	v_add_f32_dpp v0, v0, v0 row_ror:2 row_mask:0xf bank_mask:0xf bound_ctrl:1
	ds_read_b128 v[138:141], v96 offset:8064
	ds_read_b128 v[146:149], v96 offset:8576
	ds_read_b128 v[150:153], v96 offset:9088
	v_add_f32_dpp v0, v0, v0 row_ror:1 row_mask:0xf bank_mask:0xf bound_ctrl:1
	v_pk_fma_f32 v[84:85], v[0:1], v[202:203], v[236:237] op_sel_hi:[0,1,1]
	v_pk_fma_f32 v[86:87], v[0:1], v[204:205], v[238:239] op_sel_hi:[0,1,1]
	v_pk_mul_f32 v[250:251], v[84:85], v[14:15]
	v_pk_fma_f32 v[108:109], v[84:85], v[10:11], v[108:109]
	v_pk_fma_f32 v[250:251], v[86:87], v[16:17], v[250:251]
	v_pk_mul_f32 v[186:187], v[84:85], v[206:207]
	v_add_f32_e32 v0, v250, v251
	v_pk_fma_f32 v[110:111], v[86:87], v[12:13], v[110:111]
	v_pk_fma_f32 v[186:187], v[86:87], v[208:209], v[186:187]
	v_add_f32_dpp v0, v0, v0 row_ror:8 row_mask:0xf bank_mask:0xf bound_ctrl:1
	s_waitcnt lgkmcnt(6)
	v_pk_mul_f32 v[220:221], v[220:221], v[246:247] op_sel_hi:[1,0]
	v_add_f32_e32 v219, v186, v187
	v_add_f32_dpp v0, v0, v0 row_ror:4 row_mask:0xf bank_mask:0xf bound_ctrl:1
	v_pk_mul_f32 v[222:223], v[222:223], v[246:247] op_sel_hi:[1,0]
	ds_write2st64_b32 v98, v218, v219 offset0:8 offset1:12
	ds_read_b128 v[236:239], v96 offset:10176
	ds_read_b32 v234, v97 offset:9408
	ds_read_b128 v[198:201], v96 offset:9664
	v_add_f32_dpp v0, v0, v0 row_ror:2 row_mask:0xf bank_mask:0xf bound_ctrl:1
	ds_read_b128 v[194:197], v96 offset:9408
	ds_read_b128 v[202:205], v96 offset:9920
	ds_read_b128 v[206:209], v96 offset:10432
	v_add_f32_dpp v0, v0, v0 row_ror:1 row_mask:0xf bank_mask:0xf bound_ctrl:1
	v_pk_fma_f32 v[84:85], v[0:1], v[18:19], v[108:109] op_sel_hi:[0,1,1]
	v_pk_fma_f32 v[86:87], v[0:1], v[20:21], v[110:111] op_sel_hi:[0,1,1]
	v_pk_mul_f32 v[250:251], v[84:85], v[122:123]
	v_pk_fma_f32 v[220:221], v[84:85], v[118:119], v[220:221]
	v_pk_fma_f32 v[250:251], v[86:87], v[124:125], v[250:251]
	v_pk_mul_f32 v[186:187], v[84:85], v[22:23]
	v_add_f32_e32 v0, v250, v251
	v_pk_fma_f32 v[222:223], v[86:87], v[120:121], v[222:223]
	v_pk_fma_f32 v[186:187], v[86:87], v[24:25], v[186:187]
	v_add_f32_dpp v0, v0, v0 row_ror:8 row_mask:0xf bank_mask:0xf bound_ctrl:1
	s_waitcnt lgkmcnt(7)
	v_pk_mul_f32 v[224:225], v[224:225], v[214:215] op_sel_hi:[1,0]
	v_add_f32_e32 v218, v186, v187
	v_add_f32_dpp v0, v0, v0 row_ror:4 row_mask:0xf bank_mask:0xf bound_ctrl:1
	v_pk_mul_f32 v[226:227], v[226:227], v[214:215] op_sel_hi:[1,0]
	ds_read_b128 v[108:111], v96 offset:11520
	ds_read_b32 v242, v97 offset:10752
	ds_read_b128 v[14:17], v96 offset:11008
	v_add_f32_dpp v0, v0, v0 row_ror:2 row_mask:0xf bank_mask:0xf bound_ctrl:1
	ds_read_b128 v[10:13], v96 offset:10752
	ds_read_b128 v[18:21], v96 offset:11264
	ds_read_b128 v[22:25], v96 offset:11776
	v_add_f32_dpp v0, v0, v0 row_ror:1 row_mask:0xf bank_mask:0xf bound_ctrl:1
	v_pk_fma_f32 v[84:85], v[0:1], v[134:135], v[220:221] op_sel_hi:[0,1,1]
	v_pk_fma_f32 v[86:87], v[0:1], v[136:137], v[222:223] op_sel_hi:[0,1,1]
	v_pk_mul_f32 v[250:251], v[84:85], v[142:143]
	v_pk_fma_f32 v[224:225], v[84:85], v[138:139], v[224:225]
	v_pk_fma_f32 v[250:251], v[86:87], v[144:145], v[250:251]
	v_pk_mul_f32 v[186:187], v[84:85], v[230:231]
	v_add_f32_e32 v0, v250, v251
	v_pk_fma_f32 v[226:227], v[86:87], v[140:141], v[226:227]
	v_pk_fma_f32 v[186:187], v[86:87], v[232:233], v[186:187]
	v_add_f32_dpp v0, v0, v0 row_ror:8 row_mask:0xf bank_mask:0xf bound_ctrl:1
	s_waitcnt lgkmcnt(6)
	v_pk_mul_f32 v[236:237], v[236:237], v[234:235] op_sel_hi:[1,0]
	v_add_f32_e32 v219, v186, v187
	v_add_f32_dpp v0, v0, v0 row_ror:4 row_mask:0xf bank_mask:0xf bound_ctrl:1
	v_pk_mul_f32 v[238:239], v[238:239], v[234:235] op_sel_hi:[1,0]
	ds_write2st64_b32 v98, v218, v219 offset0:16 offset1:20
	ds_read_b128 v[220:223], v96 offset:12864
	ds_read_b32 v246, v97 offset:12096
	ds_read_b128 v[122:125], v96 offset:12352
	v_add_f32_dpp v0, v0, v0 row_ror:2 row_mask:0xf bank_mask:0xf bound_ctrl:1
	ds_read_b128 v[118:121], v96 offset:12096
	ds_read_b128 v[134:137], v96 offset:12608
	ds_read_b128 v[230:233], v96 offset:13120
	v_add_f32_dpp v0, v0, v0 row_ror:1 row_mask:0xf bank_mask:0xf bound_ctrl:1
	v_pk_fma_f32 v[84:85], v[0:1], v[146:147], v[224:225] op_sel_hi:[0,1,1]
	v_pk_fma_f32 v[86:87], v[0:1], v[148:149], v[226:227] op_sel_hi:[0,1,1]
	v_pk_mul_f32 v[250:251], v[84:85], v[198:199]
	v_pk_fma_f32 v[236:237], v[84:85], v[194:195], v[236:237]
	v_pk_fma_f32 v[250:251], v[86:87], v[200:201], v[250:251]
	v_pk_mul_f32 v[186:187], v[84:85], v[150:151]
	v_add_f32_e32 v0, v250, v251
	v_pk_fma_f32 v[238:239], v[86:87], v[196:197], v[238:239]
	v_pk_fma_f32 v[186:187], v[86:87], v[152:153], v[186:187]
	v_add_f32_dpp v0, v0, v0 row_ror:8 row_mask:0xf bank_mask:0xf bound_ctrl:1
	s_waitcnt lgkmcnt(7)
	v_pk_mul_f32 v[108:109], v[108:109], v[242:243] op_sel_hi:[1,0]
	v_add_f32_e32 v218, v186, v187
	v_add_f32_dpp v0, v0, v0 row_ror:4 row_mask:0xf bank_mask:0xf bound_ctrl:1
	v_pk_mul_f32 v[110:111], v[110:111], v[242:243] op_sel_hi:[1,0]
	ds_read_b128 v[224:227], v96 offset:14208
	ds_read_b32 v214, v97 offset:13440
	ds_read_b128 v[142:145], v96 offset:13696
	v_add_f32_dpp v0, v0, v0 row_ror:2 row_mask:0xf bank_mask:0xf bound_ctrl:1
	ds_read_b128 v[138:141], v96 offset:13440
	ds_read_b128 v[146:149], v96 offset:13952
	ds_read_b128 v[150:153], v96 offset:14464
	v_add_f32_dpp v0, v0, v0 row_ror:1 row_mask:0xf bank_mask:0xf bound_ctrl:1
	v_pk_fma_f32 v[84:85], v[0:1], v[202:203], v[236:237] op_sel_hi:[0,1,1]
	v_pk_fma_f32 v[86:87], v[0:1], v[204:205], v[238:239] op_sel_hi:[0,1,1]
	v_pk_mul_f32 v[250:251], v[84:85], v[14:15]
	v_pk_fma_f32 v[108:109], v[84:85], v[10:11], v[108:109]
	v_pk_fma_f32 v[250:251], v[86:87], v[16:17], v[250:251]
	v_pk_mul_f32 v[186:187], v[84:85], v[206:207]
	v_add_f32_e32 v0, v250, v251
	v_pk_fma_f32 v[110:111], v[86:87], v[12:13], v[110:111]
	v_pk_fma_f32 v[186:187], v[86:87], v[208:209], v[186:187]
	v_add_f32_dpp v0, v0, v0 row_ror:8 row_mask:0xf bank_mask:0xf bound_ctrl:1
	s_waitcnt lgkmcnt(6)
	v_pk_mul_f32 v[220:221], v[220:221], v[246:247] op_sel_hi:[1,0]
	v_add_f32_e32 v219, v186, v187
	v_add_f32_dpp v0, v0, v0 row_ror:4 row_mask:0xf bank_mask:0xf bound_ctrl:1
	v_pk_mul_f32 v[222:223], v[222:223], v[246:247] op_sel_hi:[1,0]
	ds_write2st64_b32 v98, v218, v219 offset0:24 offset1:28
	ds_read_b128 v[236:239], v96 offset:15552
	ds_read_b32 v234, v97 offset:14784
	ds_read_b128 v[198:201], v96 offset:15040
	v_add_f32_dpp v0, v0, v0 row_ror:2 row_mask:0xf bank_mask:0xf bound_ctrl:1
	ds_read_b128 v[194:197], v96 offset:14784
	ds_read_b128 v[202:205], v96 offset:15296
	ds_read_b128 v[206:209], v96 offset:15808
	v_add_f32_dpp v0, v0, v0 row_ror:1 row_mask:0xf bank_mask:0xf bound_ctrl:1
	v_pk_fma_f32 v[84:85], v[0:1], v[18:19], v[108:109] op_sel_hi:[0,1,1]
	v_pk_fma_f32 v[86:87], v[0:1], v[20:21], v[110:111] op_sel_hi:[0,1,1]
	v_pk_mul_f32 v[250:251], v[84:85], v[122:123]
	v_pk_fma_f32 v[220:221], v[84:85], v[118:119], v[220:221]
	v_pk_fma_f32 v[250:251], v[86:87], v[124:125], v[250:251]
	v_pk_mul_f32 v[186:187], v[84:85], v[22:23]
	v_add_f32_e32 v0, v250, v251
	v_pk_fma_f32 v[222:223], v[86:87], v[120:121], v[222:223]
	v_pk_fma_f32 v[186:187], v[86:87], v[24:25], v[186:187]
	v_add_f32_dpp v0, v0, v0 row_ror:8 row_mask:0xf bank_mask:0xf bound_ctrl:1
	s_waitcnt lgkmcnt(7)
	v_pk_mul_f32 v[224:225], v[224:225], v[214:215] op_sel_hi:[1,0]
	v_add_f32_e32 v218, v186, v187
	v_add_f32_dpp v0, v0, v0 row_ror:4 row_mask:0xf bank_mask:0xf bound_ctrl:1
	v_pk_mul_f32 v[226:227], v[226:227], v[214:215] op_sel_hi:[1,0]
	ds_read_b128 v[108:111], v96 offset:16896
	ds_read_b32 v242, v97 offset:16128
	ds_read_b128 v[14:17], v96 offset:16384
	v_add_f32_dpp v0, v0, v0 row_ror:2 row_mask:0xf bank_mask:0xf bound_ctrl:1
	ds_read_b128 v[10:13], v96 offset:16128
	ds_read_b128 v[18:21], v96 offset:16640
	ds_read_b128 v[22:25], v96 offset:17152
	v_add_f32_dpp v0, v0, v0 row_ror:1 row_mask:0xf bank_mask:0xf bound_ctrl:1
	v_pk_fma_f32 v[84:85], v[0:1], v[134:135], v[220:221] op_sel_hi:[0,1,1]
	v_pk_fma_f32 v[86:87], v[0:1], v[136:137], v[222:223] op_sel_hi:[0,1,1]
	v_pk_mul_f32 v[250:251], v[84:85], v[142:143]
	v_pk_fma_f32 v[224:225], v[84:85], v[138:139], v[224:225]
	v_pk_fma_f32 v[250:251], v[86:87], v[144:145], v[250:251]
	v_pk_mul_f32 v[186:187], v[84:85], v[230:231]
	v_add_f32_e32 v0, v250, v251
	v_pk_fma_f32 v[226:227], v[86:87], v[140:141], v[226:227]
	v_pk_fma_f32 v[186:187], v[86:87], v[232:233], v[186:187]
	v_add_f32_dpp v0, v0, v0 row_ror:8 row_mask:0xf bank_mask:0xf bound_ctrl:1
	s_waitcnt lgkmcnt(6)
	v_pk_mul_f32 v[236:237], v[236:237], v[234:235] op_sel_hi:[1,0]
	v_add_f32_e32 v219, v186, v187
	v_add_f32_dpp v0, v0, v0 row_ror:4 row_mask:0xf bank_mask:0xf bound_ctrl:1
	v_pk_mul_f32 v[238:239], v[238:239], v[234:235] op_sel_hi:[1,0]
	ds_write2st64_b32 v98, v218, v219 offset0:32 offset1:36
	ds_read_b128 v[220:223], v96 offset:18240
	ds_read_b32 v246, v97 offset:17472
	ds_read_b128 v[122:125], v96 offset:17728
	v_add_f32_dpp v0, v0, v0 row_ror:2 row_mask:0xf bank_mask:0xf bound_ctrl:1
	ds_read_b128 v[118:121], v96 offset:17472
	ds_read_b128 v[134:137], v96 offset:17984
	ds_read_b128 v[230:233], v96 offset:18496
	v_add_f32_dpp v0, v0, v0 row_ror:1 row_mask:0xf bank_mask:0xf bound_ctrl:1
	v_pk_fma_f32 v[84:85], v[0:1], v[146:147], v[224:225] op_sel_hi:[0,1,1]
	v_pk_fma_f32 v[86:87], v[0:1], v[148:149], v[226:227] op_sel_hi:[0,1,1]
	v_pk_mul_f32 v[250:251], v[84:85], v[198:199]
	v_pk_fma_f32 v[236:237], v[84:85], v[194:195], v[236:237]
	v_pk_fma_f32 v[250:251], v[86:87], v[200:201], v[250:251]
	v_pk_mul_f32 v[186:187], v[84:85], v[150:151]
	v_add_f32_e32 v0, v250, v251
	v_pk_fma_f32 v[238:239], v[86:87], v[196:197], v[238:239]
	v_pk_fma_f32 v[186:187], v[86:87], v[152:153], v[186:187]
	v_add_f32_dpp v0, v0, v0 row_ror:8 row_mask:0xf bank_mask:0xf bound_ctrl:1
	s_waitcnt lgkmcnt(7)
	v_pk_mul_f32 v[108:109], v[108:109], v[242:243] op_sel_hi:[1,0]
	v_add_f32_e32 v218, v186, v187
	v_add_f32_dpp v0, v0, v0 row_ror:4 row_mask:0xf bank_mask:0xf bound_ctrl:1
	v_pk_mul_f32 v[110:111], v[110:111], v[242:243] op_sel_hi:[1,0]
	ds_read_b128 v[224:227], v96 offset:19584
	ds_read_b32 v214, v97 offset:18816
	ds_read_b128 v[142:145], v96 offset:19072
	v_add_f32_dpp v0, v0, v0 row_ror:2 row_mask:0xf bank_mask:0xf bound_ctrl:1
	ds_read_b128 v[138:141], v96 offset:18816
	ds_read_b128 v[146:149], v96 offset:19328
	ds_read_b128 v[150:153], v96 offset:19840
	v_add_f32_dpp v0, v0, v0 row_ror:1 row_mask:0xf bank_mask:0xf bound_ctrl:1
	v_pk_fma_f32 v[84:85], v[0:1], v[202:203], v[236:237] op_sel_hi:[0,1,1]
	v_pk_fma_f32 v[86:87], v[0:1], v[204:205], v[238:239] op_sel_hi:[0,1,1]
	v_pk_mul_f32 v[250:251], v[84:85], v[14:15]
	v_pk_fma_f32 v[108:109], v[84:85], v[10:11], v[108:109]
	v_pk_fma_f32 v[250:251], v[86:87], v[16:17], v[250:251]
	v_pk_mul_f32 v[186:187], v[84:85], v[206:207]
	v_add_f32_e32 v0, v250, v251
	v_pk_fma_f32 v[110:111], v[86:87], v[12:13], v[110:111]
	v_pk_fma_f32 v[186:187], v[86:87], v[208:209], v[186:187]
	v_add_f32_dpp v0, v0, v0 row_ror:8 row_mask:0xf bank_mask:0xf bound_ctrl:1
	s_waitcnt lgkmcnt(6)
	v_pk_mul_f32 v[220:221], v[220:221], v[246:247] op_sel_hi:[1,0]
	v_add_f32_e32 v219, v186, v187
	v_add_f32_dpp v0, v0, v0 row_ror:4 row_mask:0xf bank_mask:0xf bound_ctrl:1
	v_pk_mul_f32 v[222:223], v[222:223], v[246:247] op_sel_hi:[1,0]
	ds_write2st64_b32 v98, v218, v219 offset0:40 offset1:44
	ds_read_b128 v[236:239], v96 offset:20928
	ds_read_b32 v234, v97 offset:20160
	ds_read_b128 v[198:201], v96 offset:20416
	v_add_f32_dpp v0, v0, v0 row_ror:2 row_mask:0xf bank_mask:0xf bound_ctrl:1
	ds_read_b128 v[194:197], v96 offset:20160
	ds_read_b128 v[202:205], v96 offset:20672
	ds_read_b128 v[206:209], v96 offset:21184
	v_add_f32_dpp v0, v0, v0 row_ror:1 row_mask:0xf bank_mask:0xf bound_ctrl:1
	v_pk_fma_f32 v[84:85], v[0:1], v[18:19], v[108:109] op_sel_hi:[0,1,1]
	v_pk_fma_f32 v[86:87], v[0:1], v[20:21], v[110:111] op_sel_hi:[0,1,1]
	v_pk_mul_f32 v[250:251], v[84:85], v[122:123]
	v_pk_fma_f32 v[220:221], v[84:85], v[118:119], v[220:221]
	v_pk_fma_f32 v[250:251], v[86:87], v[124:125], v[250:251]
	v_pk_mul_f32 v[186:187], v[84:85], v[22:23]
	v_add_f32_e32 v0, v250, v251
	v_pk_fma_f32 v[222:223], v[86:87], v[120:121], v[222:223]
	v_pk_fma_f32 v[186:187], v[86:87], v[24:25], v[186:187]
	v_add_f32_dpp v0, v0, v0 row_ror:8 row_mask:0xf bank_mask:0xf bound_ctrl:1
	s_waitcnt lgkmcnt(7)
	v_pk_mul_f32 v[224:225], v[224:225], v[214:215] op_sel_hi:[1,0]
	v_add_f32_e32 v218, v186, v187
	v_add_f32_dpp v0, v0, v0 row_ror:4 row_mask:0xf bank_mask:0xf bound_ctrl:1
	v_pk_mul_f32 v[226:227], v[226:227], v[214:215] op_sel_hi:[1,0]
	ds_read_b128 v[108:111], v96 offset:22272
	ds_read_b32 v242, v97 offset:21504
	ds_read_b128 v[14:17], v96 offset:21760
	v_add_f32_dpp v0, v0, v0 row_ror:2 row_mask:0xf bank_mask:0xf bound_ctrl:1
	ds_read_b128 v[10:13], v96 offset:21504
	ds_read_b128 v[18:21], v96 offset:22016
	ds_read_b128 v[22:25], v96 offset:22528
	v_add_f32_dpp v0, v0, v0 row_ror:1 row_mask:0xf bank_mask:0xf bound_ctrl:1
	v_pk_fma_f32 v[84:85], v[0:1], v[134:135], v[220:221] op_sel_hi:[0,1,1]
	v_pk_fma_f32 v[86:87], v[0:1], v[136:137], v[222:223] op_sel_hi:[0,1,1]
	v_pk_mul_f32 v[250:251], v[84:85], v[142:143]
	v_pk_fma_f32 v[224:225], v[84:85], v[138:139], v[224:225]
	v_pk_fma_f32 v[250:251], v[86:87], v[144:145], v[250:251]
	v_pk_mul_f32 v[186:187], v[84:85], v[230:231]
	v_add_f32_e32 v0, v250, v251
	v_pk_fma_f32 v[226:227], v[86:87], v[140:141], v[226:227]
	v_pk_fma_f32 v[186:187], v[86:87], v[232:233], v[186:187]
	v_add_f32_dpp v0, v0, v0 row_ror:8 row_mask:0xf bank_mask:0xf bound_ctrl:1
	s_waitcnt lgkmcnt(6)
	v_pk_mul_f32 v[236:237], v[236:237], v[234:235] op_sel_hi:[1,0]
	v_add_f32_e32 v219, v186, v187
	v_add_f32_dpp v0, v0, v0 row_ror:4 row_mask:0xf bank_mask:0xf bound_ctrl:1
	v_pk_mul_f32 v[238:239], v[238:239], v[234:235] op_sel_hi:[1,0]
	ds_write2st64_b32 v98, v218, v219 offset0:48 offset1:52
	ds_read_b128 v[220:223], v96 offset:23616
	ds_read_b32 v246, v97 offset:22848
	ds_read_b128 v[122:125], v96 offset:23104
	v_add_f32_dpp v0, v0, v0 row_ror:2 row_mask:0xf bank_mask:0xf bound_ctrl:1
	ds_read_b128 v[118:121], v96 offset:22848
	ds_read_b128 v[134:137], v96 offset:23360
	ds_read_b128 v[230:233], v96 offset:23872
	v_add_f32_dpp v0, v0, v0 row_ror:1 row_mask:0xf bank_mask:0xf bound_ctrl:1
	v_pk_fma_f32 v[84:85], v[0:1], v[146:147], v[224:225] op_sel_hi:[0,1,1]
	v_pk_fma_f32 v[86:87], v[0:1], v[148:149], v[226:227] op_sel_hi:[0,1,1]
	v_pk_mul_f32 v[250:251], v[84:85], v[198:199]
	v_pk_fma_f32 v[236:237], v[84:85], v[194:195], v[236:237]
	v_pk_fma_f32 v[250:251], v[86:87], v[200:201], v[250:251]
	v_pk_mul_f32 v[186:187], v[84:85], v[150:151]
	v_add_f32_e32 v0, v250, v251
	v_pk_fma_f32 v[238:239], v[86:87], v[196:197], v[238:239]
	v_pk_fma_f32 v[186:187], v[86:87], v[152:153], v[186:187]
	v_add_f32_dpp v0, v0, v0 row_ror:8 row_mask:0xf bank_mask:0xf bound_ctrl:1
	s_waitcnt lgkmcnt(7)
	v_pk_mul_f32 v[108:109], v[108:109], v[242:243] op_sel_hi:[1,0]
	v_add_f32_e32 v218, v186, v187
	v_add_f32_dpp v0, v0, v0 row_ror:4 row_mask:0xf bank_mask:0xf bound_ctrl:1
	v_pk_mul_f32 v[110:111], v[110:111], v[242:243] op_sel_hi:[1,0]
	ds_read_b128 v[224:227], v96 offset:24960
	ds_read_b32 v214, v97 offset:24192
	ds_read_b128 v[142:145], v96 offset:24448
	v_add_f32_dpp v0, v0, v0 row_ror:2 row_mask:0xf bank_mask:0xf bound_ctrl:1
	ds_read_b128 v[138:141], v96 offset:24192
	ds_read_b128 v[146:149], v96 offset:24704
	ds_read_b128 v[150:153], v96 offset:25216
	v_add_f32_dpp v0, v0, v0 row_ror:1 row_mask:0xf bank_mask:0xf bound_ctrl:1
	v_pk_fma_f32 v[84:85], v[0:1], v[202:203], v[236:237] op_sel_hi:[0,1,1]
	v_pk_fma_f32 v[86:87], v[0:1], v[204:205], v[238:239] op_sel_hi:[0,1,1]
	v_pk_mul_f32 v[250:251], v[84:85], v[14:15]
	v_pk_fma_f32 v[108:109], v[84:85], v[10:11], v[108:109]
	v_pk_fma_f32 v[250:251], v[86:87], v[16:17], v[250:251]
	v_pk_mul_f32 v[186:187], v[84:85], v[206:207]
	v_add_f32_e32 v0, v250, v251
	v_pk_fma_f32 v[110:111], v[86:87], v[12:13], v[110:111]
	v_pk_fma_f32 v[186:187], v[86:87], v[208:209], v[186:187]
	v_add_f32_dpp v0, v0, v0 row_ror:8 row_mask:0xf bank_mask:0xf bound_ctrl:1
	s_waitcnt lgkmcnt(6)
	v_pk_mul_f32 v[220:221], v[220:221], v[246:247] op_sel_hi:[1,0]
	v_add_f32_e32 v219, v186, v187
	v_add_f32_dpp v0, v0, v0 row_ror:4 row_mask:0xf bank_mask:0xf bound_ctrl:1
	v_pk_mul_f32 v[222:223], v[222:223], v[246:247] op_sel_hi:[1,0]
	ds_write2st64_b32 v98, v218, v219 offset0:56 offset1:60
	ds_read_b128 v[236:239], v96 offset:26304
	ds_read_b32 v234, v97 offset:25536
	ds_read_b128 v[198:201], v96 offset:25792
	v_add_f32_dpp v0, v0, v0 row_ror:2 row_mask:0xf bank_mask:0xf bound_ctrl:1
	ds_read_b128 v[194:197], v96 offset:25536
	ds_read_b128 v[202:205], v96 offset:26048
	ds_read_b128 v[206:209], v96 offset:26560
	v_add_f32_dpp v0, v0, v0 row_ror:1 row_mask:0xf bank_mask:0xf bound_ctrl:1
	v_pk_fma_f32 v[84:85], v[0:1], v[18:19], v[108:109] op_sel_hi:[0,1,1]
	v_pk_fma_f32 v[86:87], v[0:1], v[20:21], v[110:111] op_sel_hi:[0,1,1]
	v_pk_mul_f32 v[250:251], v[84:85], v[122:123]
	v_pk_fma_f32 v[220:221], v[84:85], v[118:119], v[220:221]
	v_pk_fma_f32 v[250:251], v[86:87], v[124:125], v[250:251]
	v_pk_mul_f32 v[186:187], v[84:85], v[22:23]
	v_add_f32_e32 v0, v250, v251
	v_pk_fma_f32 v[222:223], v[86:87], v[120:121], v[222:223]
	v_pk_fma_f32 v[186:187], v[86:87], v[24:25], v[186:187]
	v_add_f32_dpp v0, v0, v0 row_ror:8 row_mask:0xf bank_mask:0xf bound_ctrl:1
	s_waitcnt lgkmcnt(7)
	v_pk_mul_f32 v[224:225], v[224:225], v[214:215] op_sel_hi:[1,0]
	v_add_f32_e32 v218, v186, v187
	v_add_f32_dpp v0, v0, v0 row_ror:4 row_mask:0xf bank_mask:0xf bound_ctrl:1
	v_pk_mul_f32 v[226:227], v[226:227], v[214:215] op_sel_hi:[1,0]
	ds_read_b128 v[108:111], v96 offset:27648
	ds_read_b32 v242, v97 offset:26880
	ds_read_b128 v[14:17], v96 offset:27136
	v_add_f32_dpp v0, v0, v0 row_ror:2 row_mask:0xf bank_mask:0xf bound_ctrl:1
	ds_read_b128 v[10:13], v96 offset:26880
	ds_read_b128 v[18:21], v96 offset:27392
	ds_read_b128 v[22:25], v96 offset:27904
	v_add_f32_dpp v0, v0, v0 row_ror:1 row_mask:0xf bank_mask:0xf bound_ctrl:1
	v_pk_fma_f32 v[84:85], v[0:1], v[134:135], v[220:221] op_sel_hi:[0,1,1]
	v_pk_fma_f32 v[86:87], v[0:1], v[136:137], v[222:223] op_sel_hi:[0,1,1]
	v_pk_mul_f32 v[250:251], v[84:85], v[142:143]
	v_pk_fma_f32 v[224:225], v[84:85], v[138:139], v[224:225]
	v_pk_fma_f32 v[250:251], v[86:87], v[144:145], v[250:251]
	v_pk_mul_f32 v[186:187], v[84:85], v[230:231]
	v_add_f32_e32 v0, v250, v251
	v_pk_fma_f32 v[226:227], v[86:87], v[140:141], v[226:227]
	v_pk_fma_f32 v[186:187], v[86:87], v[232:233], v[186:187]
	v_add_f32_dpp v0, v0, v0 row_ror:8 row_mask:0xf bank_mask:0xf bound_ctrl:1
	s_waitcnt lgkmcnt(6)
	v_pk_mul_f32 v[236:237], v[236:237], v[234:235] op_sel_hi:[1,0]
	v_add_f32_e32 v219, v186, v187
	v_add_f32_dpp v0, v0, v0 row_ror:4 row_mask:0xf bank_mask:0xf bound_ctrl:1
	v_pk_mul_f32 v[238:239], v[238:239], v[234:235] op_sel_hi:[1,0]
	ds_write2st64_b32 v98, v218, v219 offset0:64 offset1:68
	ds_read_b128 v[220:223], v96 offset:28992
	ds_read_b32 v246, v97 offset:28224
	ds_read_b128 v[122:125], v96 offset:28480
	v_add_f32_dpp v0, v0, v0 row_ror:2 row_mask:0xf bank_mask:0xf bound_ctrl:1
	ds_read_b128 v[118:121], v96 offset:28224
	ds_read_b128 v[134:137], v96 offset:28736
	ds_read_b128 v[230:233], v96 offset:29248
	v_add_f32_dpp v0, v0, v0 row_ror:1 row_mask:0xf bank_mask:0xf bound_ctrl:1
	v_pk_fma_f32 v[84:85], v[0:1], v[146:147], v[224:225] op_sel_hi:[0,1,1]
	v_pk_fma_f32 v[86:87], v[0:1], v[148:149], v[226:227] op_sel_hi:[0,1,1]
	v_pk_mul_f32 v[250:251], v[84:85], v[198:199]
	v_pk_fma_f32 v[236:237], v[84:85], v[194:195], v[236:237]
	v_pk_fma_f32 v[250:251], v[86:87], v[200:201], v[250:251]
	v_pk_mul_f32 v[186:187], v[84:85], v[150:151]
	v_add_f32_e32 v0, v250, v251
	v_pk_fma_f32 v[238:239], v[86:87], v[196:197], v[238:239]
	v_pk_fma_f32 v[186:187], v[86:87], v[152:153], v[186:187]
	v_add_f32_dpp v0, v0, v0 row_ror:8 row_mask:0xf bank_mask:0xf bound_ctrl:1
	s_waitcnt lgkmcnt(7)
	v_pk_mul_f32 v[108:109], v[108:109], v[242:243] op_sel_hi:[1,0]
	v_add_f32_e32 v218, v186, v187
	v_add_f32_dpp v0, v0, v0 row_ror:4 row_mask:0xf bank_mask:0xf bound_ctrl:1
	v_pk_mul_f32 v[110:111], v[110:111], v[242:243] op_sel_hi:[1,0]
	ds_read_b128 v[224:227], v96 offset:30336
	ds_read_b32 v214, v97 offset:29568
	ds_read_b128 v[142:145], v96 offset:29824
	v_add_f32_dpp v0, v0, v0 row_ror:2 row_mask:0xf bank_mask:0xf bound_ctrl:1
	ds_read_b128 v[138:141], v96 offset:29568
	ds_read_b128 v[146:149], v96 offset:30080
	ds_read_b128 v[150:153], v96 offset:30592
	v_add_f32_dpp v0, v0, v0 row_ror:1 row_mask:0xf bank_mask:0xf bound_ctrl:1
	v_pk_fma_f32 v[84:85], v[0:1], v[202:203], v[236:237] op_sel_hi:[0,1,1]
	v_pk_fma_f32 v[86:87], v[0:1], v[204:205], v[238:239] op_sel_hi:[0,1,1]
	v_pk_mul_f32 v[250:251], v[84:85], v[14:15]
	v_pk_fma_f32 v[108:109], v[84:85], v[10:11], v[108:109]
	v_pk_fma_f32 v[250:251], v[86:87], v[16:17], v[250:251]
	v_pk_mul_f32 v[186:187], v[84:85], v[206:207]
	v_add_f32_e32 v0, v250, v251
	v_pk_fma_f32 v[110:111], v[86:87], v[12:13], v[110:111]
	v_pk_fma_f32 v[186:187], v[86:87], v[208:209], v[186:187]
	v_add_f32_dpp v0, v0, v0 row_ror:8 row_mask:0xf bank_mask:0xf bound_ctrl:1
	s_waitcnt lgkmcnt(6)
	v_pk_mul_f32 v[220:221], v[220:221], v[246:247] op_sel_hi:[1,0]
	v_add_f32_e32 v219, v186, v187
	v_add_f32_dpp v0, v0, v0 row_ror:4 row_mask:0xf bank_mask:0xf bound_ctrl:1
	v_pk_mul_f32 v[222:223], v[222:223], v[246:247] op_sel_hi:[1,0]
	ds_write2st64_b32 v98, v218, v219 offset0:72 offset1:76
	ds_read_b128 v[236:239], v96 offset:31680
	ds_read_b32 v234, v97 offset:30912
	ds_read_b128 v[198:201], v96 offset:31168
	v_add_f32_dpp v0, v0, v0 row_ror:2 row_mask:0xf bank_mask:0xf bound_ctrl:1
	ds_read_b128 v[194:197], v96 offset:30912
	ds_read_b128 v[202:205], v96 offset:31424
	ds_read_b128 v[206:209], v96 offset:31936
	v_add_f32_dpp v0, v0, v0 row_ror:1 row_mask:0xf bank_mask:0xf bound_ctrl:1
	v_pk_fma_f32 v[84:85], v[0:1], v[18:19], v[108:109] op_sel_hi:[0,1,1]
	v_pk_fma_f32 v[86:87], v[0:1], v[20:21], v[110:111] op_sel_hi:[0,1,1]
	v_pk_mul_f32 v[250:251], v[84:85], v[122:123]
	v_pk_fma_f32 v[220:221], v[84:85], v[118:119], v[220:221]
	v_pk_fma_f32 v[250:251], v[86:87], v[124:125], v[250:251]
	v_pk_mul_f32 v[186:187], v[84:85], v[22:23]
	v_add_f32_e32 v0, v250, v251
	v_pk_fma_f32 v[222:223], v[86:87], v[120:121], v[222:223]
	v_pk_fma_f32 v[186:187], v[86:87], v[24:25], v[186:187]
	v_add_f32_dpp v0, v0, v0 row_ror:8 row_mask:0xf bank_mask:0xf bound_ctrl:1
	s_waitcnt lgkmcnt(7)
	v_pk_mul_f32 v[224:225], v[224:225], v[214:215] op_sel_hi:[1,0]
	v_add_f32_e32 v218, v186, v187
	v_add_f32_dpp v0, v0, v0 row_ror:4 row_mask:0xf bank_mask:0xf bound_ctrl:1
	v_pk_mul_f32 v[226:227], v[226:227], v[214:215] op_sel_hi:[1,0]
	ds_read_b128 v[108:111], v96 offset:33024
	ds_read_b32 v242, v97 offset:32256
	ds_read_b128 v[14:17], v96 offset:32512
	v_add_f32_dpp v0, v0, v0 row_ror:2 row_mask:0xf bank_mask:0xf bound_ctrl:1
	ds_read_b128 v[10:13], v96 offset:32256
	ds_read_b128 v[18:21], v96 offset:32768
	ds_read_b128 v[22:25], v96 offset:33280
	v_add_f32_dpp v0, v0, v0 row_ror:1 row_mask:0xf bank_mask:0xf bound_ctrl:1
	v_pk_fma_f32 v[84:85], v[0:1], v[134:135], v[220:221] op_sel_hi:[0,1,1]
	v_pk_fma_f32 v[86:87], v[0:1], v[136:137], v[222:223] op_sel_hi:[0,1,1]
	v_pk_mul_f32 v[250:251], v[84:85], v[142:143]
	v_pk_fma_f32 v[224:225], v[84:85], v[138:139], v[224:225]
	v_pk_fma_f32 v[250:251], v[86:87], v[144:145], v[250:251]
	v_pk_mul_f32 v[186:187], v[84:85], v[230:231]
	v_add_f32_e32 v0, v250, v251
	v_pk_fma_f32 v[226:227], v[86:87], v[140:141], v[226:227]
	v_pk_fma_f32 v[186:187], v[86:87], v[232:233], v[186:187]
	v_add_f32_dpp v0, v0, v0 row_ror:8 row_mask:0xf bank_mask:0xf bound_ctrl:1
	s_waitcnt lgkmcnt(6)
	v_pk_mul_f32 v[236:237], v[236:237], v[234:235] op_sel_hi:[1,0]
	v_add_f32_e32 v219, v186, v187
	v_add_f32_dpp v0, v0, v0 row_ror:4 row_mask:0xf bank_mask:0xf bound_ctrl:1
	v_pk_mul_f32 v[238:239], v[238:239], v[234:235] op_sel_hi:[1,0]
	ds_write2st64_b32 v98, v218, v219 offset0:80 offset1:84
	ds_read_b128 v[220:223], v96 offset:34368
	ds_read_b32 v246, v97 offset:33600
	ds_read_b128 v[122:125], v96 offset:33856
	v_add_f32_dpp v0, v0, v0 row_ror:2 row_mask:0xf bank_mask:0xf bound_ctrl:1
	ds_read_b128 v[118:121], v96 offset:33600
	ds_read_b128 v[134:137], v96 offset:34112
	ds_read_b128 v[230:233], v96 offset:34624
	v_add_f32_dpp v0, v0, v0 row_ror:1 row_mask:0xf bank_mask:0xf bound_ctrl:1
	v_pk_fma_f32 v[84:85], v[0:1], v[146:147], v[224:225] op_sel_hi:[0,1,1]
	v_pk_fma_f32 v[86:87], v[0:1], v[148:149], v[226:227] op_sel_hi:[0,1,1]
	v_pk_mul_f32 v[250:251], v[84:85], v[198:199]
	v_pk_fma_f32 v[236:237], v[84:85], v[194:195], v[236:237]
	v_pk_fma_f32 v[250:251], v[86:87], v[200:201], v[250:251]
	v_pk_mul_f32 v[186:187], v[84:85], v[150:151]
	v_add_f32_e32 v0, v250, v251
	v_pk_fma_f32 v[238:239], v[86:87], v[196:197], v[238:239]
	v_pk_fma_f32 v[186:187], v[86:87], v[152:153], v[186:187]
	v_add_f32_dpp v0, v0, v0 row_ror:8 row_mask:0xf bank_mask:0xf bound_ctrl:1
	s_waitcnt lgkmcnt(7)
	v_pk_mul_f32 v[108:109], v[108:109], v[242:243] op_sel_hi:[1,0]
	v_add_f32_e32 v218, v186, v187
	v_add_f32_dpp v0, v0, v0 row_ror:4 row_mask:0xf bank_mask:0xf bound_ctrl:1
	v_pk_mul_f32 v[110:111], v[110:111], v[242:243] op_sel_hi:[1,0]
	ds_read_b128 v[224:227], v96 offset:35712
	ds_read_b32 v214, v97 offset:34944
	ds_read_b128 v[142:145], v96 offset:35200
	v_add_f32_dpp v0, v0, v0 row_ror:2 row_mask:0xf bank_mask:0xf bound_ctrl:1
	ds_read_b128 v[138:141], v96 offset:34944
	ds_read_b128 v[146:149], v96 offset:35456
	ds_read_b128 v[150:153], v96 offset:35968
	v_add_f32_dpp v0, v0, v0 row_ror:1 row_mask:0xf bank_mask:0xf bound_ctrl:1
	v_pk_fma_f32 v[84:85], v[0:1], v[202:203], v[236:237] op_sel_hi:[0,1,1]
	v_pk_fma_f32 v[86:87], v[0:1], v[204:205], v[238:239] op_sel_hi:[0,1,1]
	v_pk_mul_f32 v[250:251], v[84:85], v[14:15]
	v_pk_fma_f32 v[108:109], v[84:85], v[10:11], v[108:109]
	v_pk_fma_f32 v[250:251], v[86:87], v[16:17], v[250:251]
	v_pk_mul_f32 v[186:187], v[84:85], v[206:207]
	v_add_f32_e32 v0, v250, v251
	v_pk_fma_f32 v[110:111], v[86:87], v[12:13], v[110:111]
	v_pk_fma_f32 v[186:187], v[86:87], v[208:209], v[186:187]
	v_add_f32_dpp v0, v0, v0 row_ror:8 row_mask:0xf bank_mask:0xf bound_ctrl:1
	s_waitcnt lgkmcnt(6)
	v_pk_mul_f32 v[220:221], v[220:221], v[246:247] op_sel_hi:[1,0]
	v_add_f32_e32 v219, v186, v187
	v_add_f32_dpp v0, v0, v0 row_ror:4 row_mask:0xf bank_mask:0xf bound_ctrl:1
	v_pk_mul_f32 v[222:223], v[222:223], v[246:247] op_sel_hi:[1,0]
	ds_write2st64_b32 v98, v218, v219 offset0:88 offset1:92
	ds_read_b128 v[236:239], v96 offset:37056
	ds_read_b32 v234, v97 offset:36288
	ds_read_b128 v[198:201], v96 offset:36544
	v_add_f32_dpp v0, v0, v0 row_ror:2 row_mask:0xf bank_mask:0xf bound_ctrl:1
	ds_read_b128 v[194:197], v96 offset:36288
	ds_read_b128 v[202:205], v96 offset:36800
	ds_read_b128 v[206:209], v96 offset:37312
	v_add_f32_dpp v0, v0, v0 row_ror:1 row_mask:0xf bank_mask:0xf bound_ctrl:1
	v_pk_fma_f32 v[84:85], v[0:1], v[18:19], v[108:109] op_sel_hi:[0,1,1]
	v_pk_fma_f32 v[86:87], v[0:1], v[20:21], v[110:111] op_sel_hi:[0,1,1]
	v_pk_mul_f32 v[250:251], v[84:85], v[122:123]
	v_pk_fma_f32 v[220:221], v[84:85], v[118:119], v[220:221]
	v_pk_fma_f32 v[250:251], v[86:87], v[124:125], v[250:251]
	v_pk_mul_f32 v[186:187], v[84:85], v[22:23]
	v_add_f32_e32 v0, v250, v251
	v_pk_fma_f32 v[222:223], v[86:87], v[120:121], v[222:223]
	v_pk_fma_f32 v[186:187], v[86:87], v[24:25], v[186:187]
	v_add_f32_dpp v0, v0, v0 row_ror:8 row_mask:0xf bank_mask:0xf bound_ctrl:1
	s_waitcnt lgkmcnt(7)
	v_pk_mul_f32 v[224:225], v[224:225], v[214:215] op_sel_hi:[1,0]
	v_add_f32_e32 v218, v186, v187
	v_add_f32_dpp v0, v0, v0 row_ror:4 row_mask:0xf bank_mask:0xf bound_ctrl:1
	v_pk_mul_f32 v[226:227], v[226:227], v[214:215] op_sel_hi:[1,0]
	ds_read_b128 v[108:111], v96 offset:38400
	ds_read_b32 v242, v97 offset:37632
	ds_read_b128 v[14:17], v96 offset:37888
	v_add_f32_dpp v0, v0, v0 row_ror:2 row_mask:0xf bank_mask:0xf bound_ctrl:1
	ds_read_b128 v[10:13], v96 offset:37632
	ds_read_b128 v[18:21], v96 offset:38144
	ds_read_b128 v[22:25], v96 offset:38656
	v_add_f32_dpp v0, v0, v0 row_ror:1 row_mask:0xf bank_mask:0xf bound_ctrl:1
	v_pk_fma_f32 v[84:85], v[0:1], v[134:135], v[220:221] op_sel_hi:[0,1,1]
	v_pk_fma_f32 v[86:87], v[0:1], v[136:137], v[222:223] op_sel_hi:[0,1,1]
	v_pk_mul_f32 v[250:251], v[84:85], v[142:143]
	v_pk_fma_f32 v[224:225], v[84:85], v[138:139], v[224:225]
	v_pk_fma_f32 v[250:251], v[86:87], v[144:145], v[250:251]
	v_pk_mul_f32 v[186:187], v[84:85], v[230:231]
	v_add_f32_e32 v0, v250, v251
	v_pk_fma_f32 v[226:227], v[86:87], v[140:141], v[226:227]
	v_pk_fma_f32 v[186:187], v[86:87], v[232:233], v[186:187]
	v_add_f32_dpp v0, v0, v0 row_ror:8 row_mask:0xf bank_mask:0xf bound_ctrl:1
	s_waitcnt lgkmcnt(6)
	v_pk_mul_f32 v[236:237], v[236:237], v[234:235] op_sel_hi:[1,0]
	v_add_f32_e32 v219, v186, v187
	v_add_f32_dpp v0, v0, v0 row_ror:4 row_mask:0xf bank_mask:0xf bound_ctrl:1
	v_pk_mul_f32 v[238:239], v[238:239], v[234:235] op_sel_hi:[1,0]
	ds_write2st64_b32 v98, v218, v219 offset0:96 offset1:100
	ds_read_b128 v[220:223], v96 offset:39744
	ds_read_b32 v246, v97 offset:38976
	ds_read_b128 v[122:125], v96 offset:39232
	v_add_f32_dpp v0, v0, v0 row_ror:2 row_mask:0xf bank_mask:0xf bound_ctrl:1
	ds_read_b128 v[118:121], v96 offset:38976
	ds_read_b128 v[134:137], v96 offset:39488
	ds_read_b128 v[230:233], v96 offset:40000
	v_add_f32_dpp v0, v0, v0 row_ror:1 row_mask:0xf bank_mask:0xf bound_ctrl:1
	v_pk_fma_f32 v[84:85], v[0:1], v[146:147], v[224:225] op_sel_hi:[0,1,1]
	v_pk_fma_f32 v[86:87], v[0:1], v[148:149], v[226:227] op_sel_hi:[0,1,1]
	v_pk_mul_f32 v[250:251], v[84:85], v[198:199]
	v_pk_fma_f32 v[236:237], v[84:85], v[194:195], v[236:237]
	v_pk_fma_f32 v[250:251], v[86:87], v[200:201], v[250:251]
	v_pk_mul_f32 v[186:187], v[84:85], v[150:151]
	v_add_f32_e32 v0, v250, v251
	v_pk_fma_f32 v[238:239], v[86:87], v[196:197], v[238:239]
	v_pk_fma_f32 v[186:187], v[86:87], v[152:153], v[186:187]
	v_add_f32_dpp v0, v0, v0 row_ror:8 row_mask:0xf bank_mask:0xf bound_ctrl:1
	s_waitcnt lgkmcnt(7)
	v_pk_mul_f32 v[108:109], v[108:109], v[242:243] op_sel_hi:[1,0]
	v_add_f32_e32 v218, v186, v187
	v_add_f32_dpp v0, v0, v0 row_ror:4 row_mask:0xf bank_mask:0xf bound_ctrl:1
	v_pk_mul_f32 v[110:111], v[110:111], v[242:243] op_sel_hi:[1,0]
	ds_read_b128 v[224:227], v96 offset:41088
	ds_read_b32 v214, v97 offset:40320
	ds_read_b128 v[142:145], v96 offset:40576
	v_add_f32_dpp v0, v0, v0 row_ror:2 row_mask:0xf bank_mask:0xf bound_ctrl:1
	ds_read_b128 v[138:141], v96 offset:40320
	ds_read_b128 v[146:149], v96 offset:40832
	ds_read_b128 v[150:153], v96 offset:41344
	v_add_f32_dpp v0, v0, v0 row_ror:1 row_mask:0xf bank_mask:0xf bound_ctrl:1
	v_pk_fma_f32 v[84:85], v[0:1], v[202:203], v[236:237] op_sel_hi:[0,1,1]
	v_pk_fma_f32 v[86:87], v[0:1], v[204:205], v[238:239] op_sel_hi:[0,1,1]
	v_pk_mul_f32 v[250:251], v[84:85], v[14:15]
	v_pk_fma_f32 v[108:109], v[84:85], v[10:11], v[108:109]
	v_pk_fma_f32 v[250:251], v[86:87], v[16:17], v[250:251]
	v_pk_mul_f32 v[186:187], v[84:85], v[206:207]
	v_add_f32_e32 v0, v250, v251
	v_pk_fma_f32 v[110:111], v[86:87], v[12:13], v[110:111]
	v_pk_fma_f32 v[186:187], v[86:87], v[208:209], v[186:187]
	v_add_f32_dpp v0, v0, v0 row_ror:8 row_mask:0xf bank_mask:0xf bound_ctrl:1
	s_waitcnt lgkmcnt(6)
	v_pk_mul_f32 v[220:221], v[220:221], v[246:247] op_sel_hi:[1,0]
	v_add_f32_e32 v219, v186, v187
	v_add_f32_dpp v0, v0, v0 row_ror:4 row_mask:0xf bank_mask:0xf bound_ctrl:1
	v_pk_mul_f32 v[222:223], v[222:223], v[246:247] op_sel_hi:[1,0]
	ds_write2st64_b32 v98, v218, v219 offset0:104 offset1:108
	ds_read_b128 v[236:239], v96 offset:42432
	ds_read_b32 v234, v97 offset:41664
	ds_read_b128 v[198:201], v96 offset:41920
	v_add_f32_dpp v0, v0, v0 row_ror:2 row_mask:0xf bank_mask:0xf bound_ctrl:1
	ds_read_b128 v[194:197], v96 offset:41664
	ds_read_b128 v[202:205], v96 offset:42176
	ds_read_b128 v[206:209], v96 offset:42688
	v_add_f32_dpp v0, v0, v0 row_ror:1 row_mask:0xf bank_mask:0xf bound_ctrl:1
	v_pk_fma_f32 v[84:85], v[0:1], v[18:19], v[108:109] op_sel_hi:[0,1,1]
	v_pk_fma_f32 v[86:87], v[0:1], v[20:21], v[110:111] op_sel_hi:[0,1,1]
	v_pk_mul_f32 v[250:251], v[84:85], v[122:123]
	v_pk_fma_f32 v[220:221], v[84:85], v[118:119], v[220:221]
	v_pk_fma_f32 v[250:251], v[86:87], v[124:125], v[250:251]
	v_pk_mul_f32 v[186:187], v[84:85], v[22:23]
	v_add_f32_e32 v0, v250, v251
	v_pk_fma_f32 v[222:223], v[86:87], v[120:121], v[222:223]
	v_pk_fma_f32 v[186:187], v[86:87], v[24:25], v[186:187]
	v_add_f32_dpp v0, v0, v0 row_ror:8 row_mask:0xf bank_mask:0xf bound_ctrl:1
	s_waitcnt lgkmcnt(7)
	v_pk_mul_f32 v[224:225], v[224:225], v[214:215] op_sel_hi:[1,0]
	v_add_f32_e32 v218, v186, v187
	v_add_f32_dpp v0, v0, v0 row_ror:4 row_mask:0xf bank_mask:0xf bound_ctrl:1
	v_pk_mul_f32 v[226:227], v[226:227], v[214:215] op_sel_hi:[1,0]
	s_nop 0
	v_add_f32_dpp v0, v0, v0 row_ror:2 row_mask:0xf bank_mask:0xf bound_ctrl:1
	s_nop 1
	v_add_f32_dpp v0, v0, v0 row_ror:1 row_mask:0xf bank_mask:0xf bound_ctrl:1
	v_pk_fma_f32 v[84:85], v[0:1], v[134:135], v[220:221] op_sel_hi:[0,1,1]
	v_pk_fma_f32 v[86:87], v[0:1], v[136:137], v[222:223] op_sel_hi:[0,1,1]
	v_pk_mul_f32 v[250:251], v[84:85], v[142:143]
	v_pk_fma_f32 v[224:225], v[84:85], v[138:139], v[224:225]
	v_pk_fma_f32 v[250:251], v[86:87], v[144:145], v[250:251]
	v_pk_mul_f32 v[186:187], v[84:85], v[230:231]
	v_add_f32_e32 v0, v250, v251
	v_pk_fma_f32 v[226:227], v[86:87], v[140:141], v[226:227]
	v_pk_fma_f32 v[186:187], v[86:87], v[232:233], v[186:187]
	v_add_f32_dpp v0, v0, v0 row_ror:8 row_mask:0xf bank_mask:0xf bound_ctrl:1
	s_waitcnt lgkmcnt(0)
	v_pk_mul_f32 v[236:237], v[236:237], v[234:235] op_sel_hi:[1,0]
	v_add_f32_e32 v219, v186, v187
	v_add_f32_dpp v0, v0, v0 row_ror:4 row_mask:0xf bank_mask:0xf bound_ctrl:1
	v_pk_mul_f32 v[238:239], v[238:239], v[234:235] op_sel_hi:[1,0]
	ds_write2st64_b32 v98, v218, v219 offset0:112 offset1:116
	v_add_f32_dpp v0, v0, v0 row_ror:2 row_mask:0xf bank_mask:0xf bound_ctrl:1
	s_nop 1
	v_add_f32_dpp v0, v0, v0 row_ror:1 row_mask:0xf bank_mask:0xf bound_ctrl:1
	v_pk_fma_f32 v[84:85], v[0:1], v[146:147], v[224:225] op_sel_hi:[0,1,1]
	v_pk_fma_f32 v[86:87], v[0:1], v[148:149], v[226:227] op_sel_hi:[0,1,1]
	v_pk_mul_f32 v[250:251], v[84:85], v[198:199]
	v_pk_fma_f32 v[236:237], v[84:85], v[194:195], v[236:237]
	v_pk_fma_f32 v[250:251], v[86:87], v[200:201], v[250:251]
	v_pk_mul_f32 v[186:187], v[84:85], v[150:151]
	v_add_f32_e32 v0, v250, v251
	v_pk_fma_f32 v[238:239], v[86:87], v[196:197], v[238:239]
	v_pk_fma_f32 v[186:187], v[86:87], v[152:153], v[186:187]
	v_add_f32_dpp v0, v0, v0 row_ror:8 row_mask:0xf bank_mask:0xf bound_ctrl:1
	v_add_f32_e32 v218, v186, v187
	s_nop 0
	v_add_f32_dpp v0, v0, v0 row_ror:4 row_mask:0xf bank_mask:0xf bound_ctrl:1
	s_nop 1
	v_add_f32_dpp v0, v0, v0 row_ror:2 row_mask:0xf bank_mask:0xf bound_ctrl:1
	s_nop 1
	v_add_f32_dpp v0, v0, v0 row_ror:1 row_mask:0xf bank_mask:0xf bound_ctrl:1
	v_pk_fma_f32 v[84:85], v[0:1], v[202:203], v[236:237] op_sel_hi:[0,1,1]
	v_pk_fma_f32 v[86:87], v[0:1], v[204:205], v[238:239] op_sel_hi:[0,1,1]
	v_pk_mul_f32 v[186:187], v[84:85], v[206:207]
	s_nop 0
	v_pk_fma_f32 v[186:187], v[86:87], v[208:209], v[186:187]
	s_nop 0
	v_add_f32_e32 v219, v186, v187
	ds_write2st64_b32 v98, v218, v219 offset0:120 offset1:124
